# GEMM1 epilogue activations: the gelu and silu element math rewritten with packed f32 ops on register pairs (same operation order and rounding), about a third fewer VALU instructions
# speedup vs baseline: 1.0070x; 1.0043x over previous
.LBB0_340:
	s_and_b64 vcc, exec, s[22:23]
	s_cbranch_vccz .LBB0_339
	s_lshl_b32 s1, s21, 1
	s_lshr_b32 s1, 0x11819, s1
	s_ashr_i32 s15, s14, 31
	s_and_b32 s16, s1, 3
	v_or_b32_e32 v174, s0, v205
	s_lshl_b64 s[0:1], s[14:15], 2
	s_add_u32 s0, s44, s0
	v_add_u32_e32 v176, 0x80, v172
	s_addc_u32 s1, s45, s1
	v_ashrrev_i32_e32 v175, 31, v174
	v_ashrrev_i32_e32 v177, 31, v176
	v_ashrrev_i32_e32 v173, 31, v172
	s_add_i32 s98, s80, 0x20000
	s_add_i32 s99, s80, 0x22000
	v_lshl_add_u32 v146, v193, 2, s98
	v_lshl_add_u32 v147, v205, 2, s99
	s_nop 0
	ds_read_b128 v[66:69], v147 offset:16
	ds_read_b128 v[70:73], v147
	ds_read_b32 v170, v146
	ds_read_b32 v168, v146 offset:64
	ds_read_b32 v166, v146 offset:128
	ds_read_b32 v164, v146 offset:192
	ds_read_b32 v171, v146 offset:512
	ds_read_b32 v169, v146 offset:576
	ds_read_b32 v167, v146 offset:640
	ds_read_b32 v165, v146 offset:704
	ds_read_b128 v[50:53], v147 offset:528
	ds_read_b128 v[54:57], v147 offset:512
	s_waitcnt lgkmcnt(0)
	v_fmamk_f32 v146, v170, 0x3a800000, v235
	v_rsq_f32_e32 v178, v146
	s_cmp_lt_i32 s16, 2
	s_mov_b64 s[14:15], -1
	v_pk_fma_f32 v[138:139], v[178:179], v[138:139], v[66:67] op_sel_hi:[0,1,1]
	v_pk_fma_f32 v[142:143], v[178:179], v[142:143], v[70:71] op_sel_hi:[0,1,1]
	v_pk_fma_f32 v[144:145], v[178:179], v[144:145], v[72:73] op_sel_hi:[0,1,1]
	v_pk_fma_f32 v[140:141], v[178:179], v[140:141], v[68:69] op_sel_hi:[0,1,1]
	s_cbranch_scc1 .LBB0_345
	v_mov_b64_e32 v[152:153], v[140:141]
	v_mov_b64_e32 v[148:149], v[144:145]
	s_cmp_eq_u32 s16, 2
	v_mov_b64_e32 v[150:151], v[138:139]
	v_mov_b64_e32 v[146:147], v[142:143]
	s_cbranch_scc0 .LBB0_344
	s_mov_b32 s98, 0x3d372713
	s_mov_b32 s99, 0x3fcc422a
	s_mov_b32 s100, 0xbfb8aa3b
	s_mov_b32 s101, 1.0
	v_pk_mul_f32 v[146:147], v[142:143], s[98:99] op_sel_hi:[1,0]
	v_pk_mul_f32 v[148:149], v[144:145], s[98:99] op_sel_hi:[1,0]
	v_pk_mul_f32 v[152:153], v[140:141], s[98:99] op_sel_hi:[1,0]
	v_pk_mul_f32 v[150:151], v[138:139], s[98:99] op_sel_hi:[1,0]
	v_pk_mul_f32 v[146:147], v[142:143], v[146:147]
	v_pk_mul_f32 v[148:149], v[144:145], v[148:149]
	v_pk_mul_f32 v[152:153], v[140:141], v[152:153]
	v_pk_mul_f32 v[150:151], v[138:139], v[150:151]
	v_pk_fma_f32 v[146:147], v[142:143], v[146:147], v[142:143]
	v_pk_fma_f32 v[148:149], v[144:145], v[148:149], v[144:145]
	v_pk_fma_f32 v[152:153], v[140:141], v[152:153], v[140:141]
	v_pk_fma_f32 v[150:151], v[138:139], v[150:151], v[138:139]
	v_pk_mul_f32 v[146:147], v[146:147], s[98:99] op_sel:[0,1] op_sel_hi:[1,1]
	v_pk_mul_f32 v[148:149], v[148:149], s[98:99] op_sel:[0,1] op_sel_hi:[1,1]
	v_pk_mul_f32 v[152:153], v[152:153], s[98:99] op_sel:[0,1] op_sel_hi:[1,1]
	v_pk_mul_f32 v[150:151], v[150:151], s[98:99] op_sel:[0,1] op_sel_hi:[1,1]
	v_pk_mul_f32 v[146:147], v[146:147], s[100:101] op_sel_hi:[1,0]
	v_pk_mul_f32 v[148:149], v[148:149], s[100:101] op_sel_hi:[1,0]
	v_pk_mul_f32 v[152:153], v[152:153], s[100:101] op_sel_hi:[1,0]
	v_pk_mul_f32 v[150:151], v[150:151], s[100:101] op_sel_hi:[1,0]
	v_exp_f32_e32 v146, v146
	v_exp_f32_e32 v147, v147
	v_exp_f32_e32 v148, v148
	v_exp_f32_e32 v149, v149
	v_exp_f32_e32 v152, v152
	v_exp_f32_e32 v153, v153
	v_exp_f32_e32 v150, v150
	v_exp_f32_e32 v151, v151
	v_pk_add_f32 v[146:147], v[146:147], s[100:101] op_sel:[0,1] op_sel_hi:[1,1]
	v_pk_add_f32 v[148:149], v[148:149], s[100:101] op_sel:[0,1] op_sel_hi:[1,1]
	v_pk_add_f32 v[152:153], v[152:153], s[100:101] op_sel:[0,1] op_sel_hi:[1,1]
	v_pk_add_f32 v[150:151], v[150:151], s[100:101] op_sel:[0,1] op_sel_hi:[1,1]
	v_rcp_f32_e32 v146, v146
	v_rcp_f32_e32 v147, v147
	v_rcp_f32_e32 v148, v148
	v_rcp_f32_e32 v149, v149
	v_rcp_f32_e32 v152, v152
	v_rcp_f32_e32 v153, v153
	v_rcp_f32_e32 v150, v150
	v_rcp_f32_e32 v151, v151
	v_pk_mul_f32 v[146:147], v[142:143], v[146:147]
	v_pk_mul_f32 v[148:149], v[144:145], v[148:149]
	v_pk_mul_f32 v[152:153], v[140:141], v[152:153]
	v_pk_mul_f32 v[150:151], v[138:139], v[150:151]

.LBB0_345:
	s_andn2_b64 vcc, exec, s[14:15]
	s_cbranch_vccnz .LBB0_349
	s_cmp_eq_u32 s16, 1
	s_cbranch_scc0 .LBB0_348
	s_mov_b32 s100, 0xbfb8aa3b
	s_mov_b32 s101, 1.0
	v_pk_mul_f32 v[146:147], v[142:143], s[100:101] op_sel_hi:[1,0]
	v_pk_mul_f32 v[148:149], v[138:139], s[100:101] op_sel_hi:[1,0]
	v_pk_mul_f32 v[150:151], v[144:145], s[100:101] op_sel_hi:[1,0]
	v_pk_mul_f32 v[152:153], v[140:141], s[100:101] op_sel_hi:[1,0]
	v_exp_f32_e32 v146, v146
	v_exp_f32_e32 v147, v147
	v_exp_f32_e32 v148, v148
	v_exp_f32_e32 v149, v149
	v_exp_f32_e32 v150, v150
	v_exp_f32_e32 v151, v151
	v_exp_f32_e32 v152, v152
	v_exp_f32_e32 v153, v153
	v_pk_add_f32 v[146:147], v[146:147], s[100:101] op_sel:[0,1] op_sel_hi:[1,1]
	v_pk_add_f32 v[148:149], v[148:149], s[100:101] op_sel:[0,1] op_sel_hi:[1,1]
	v_pk_add_f32 v[150:151], v[150:151], s[100:101] op_sel:[0,1] op_sel_hi:[1,1]
	v_pk_add_f32 v[152:153], v[152:153], s[100:101] op_sel:[0,1] op_sel_hi:[1,1]
	v_rcp_f32_e32 v146, v146
	v_rcp_f32_e32 v147, v147
	v_rcp_f32_e32 v148, v148
	v_rcp_f32_e32 v149, v149
	v_rcp_f32_e32 v150, v150
	v_rcp_f32_e32 v151, v151
	v_rcp_f32_e32 v152, v152
	v_rcp_f32_e32 v153, v153
	v_pk_mul_f32 v[142:143], v[142:143], v[146:147]
	v_pk_mul_f32 v[138:139], v[138:139], v[148:149]
	v_pk_mul_f32 v[144:145], v[144:145], v[150:151]
	v_pk_mul_f32 v[140:141], v[140:141], v[152:153]

.LBB0_349:
	v_mov_b64_e32 v[138:139], s[68:69]
	v_mad_i64_i32 v[138:139], s[0:1], v172, s9, v[138:139]
	v_lshl_add_u64 v[180:181], v[174:175], 1, v[138:139]
	v_cvt_pk_bf16_f32 v138, v146, v147
	v_cvt_pk_bf16_f32 v139, v148, v149
	v_cvt_pk_bf16_f32 v140, v150, v151
	v_cvt_pk_bf16_f32 v141, v152, v153
	global_store_dwordx4 v[180:181], v[138:141], off nt
	v_mov_b32_e32 v179, v178
	v_pk_fma_f32 v[134:135], v[178:179], v[134:135], v[54:55]
	v_mov_b32_e32 v138, v178
	v_mov_b32_e32 v139, v178
	v_pk_fma_f32 v[136:137], v[138:139], v[136:137], v[56:57]
	v_pk_fma_f32 v[132:133], v[138:139], v[132:133], v[52:53]
	v_pk_fma_f32 v[130:131], v[178:179], v[130:131], v[50:51]
	s_cmp_lt_i32 s16, 2
	s_mov_b64 s[14:15], -1
	s_cbranch_scc1 .LBB0_353
	v_mov_b64_e32 v[144:145], v[132:133]
	v_mov_b64_e32 v[140:141], v[136:137]
	s_cmp_eq_u32 s16, 2
	v_mov_b64_e32 v[142:143], v[130:131]
	v_mov_b64_e32 v[138:139], v[134:135]
	s_cbranch_scc0 .LBB0_352
	s_mov_b32 s98, 0x3d372713
	s_mov_b32 s99, 0x3fcc422a
	s_mov_b32 s100, 0xbfb8aa3b
	s_mov_b32 s101, 1.0
	v_pk_mul_f32 v[138:139], v[134:135], s[98:99] op_sel_hi:[1,0]
	v_pk_mul_f32 v[140:141], v[136:137], s[98:99] op_sel_hi:[1,0]
	v_pk_mul_f32 v[144:145], v[132:133], s[98:99] op_sel_hi:[1,0]
	v_pk_mul_f32 v[142:143], v[130:131], s[98:99] op_sel_hi:[1,0]
	v_pk_mul_f32 v[138:139], v[134:135], v[138:139]
	v_pk_mul_f32 v[140:141], v[136:137], v[140:141]
	v_pk_mul_f32 v[144:145], v[132:133], v[144:145]
	v_pk_mul_f32 v[142:143], v[130:131], v[142:143]
	v_pk_fma_f32 v[138:139], v[134:135], v[138:139], v[134:135]
	v_pk_fma_f32 v[140:141], v[136:137], v[140:141], v[136:137]
	v_pk_fma_f32 v[144:145], v[132:133], v[144:145], v[132:133]
	v_pk_fma_f32 v[142:143], v[130:131], v[142:143], v[130:131]
	v_pk_mul_f32 v[138:139], v[138:139], s[98:99] op_sel:[0,1] op_sel_hi:[1,1]
	v_pk_mul_f32 v[140:141], v[140:141], s[98:99] op_sel:[0,1] op_sel_hi:[1,1]
	v_pk_mul_f32 v[144:145], v[144:145], s[98:99] op_sel:[0,1] op_sel_hi:[1,1]
	v_pk_mul_f32 v[142:143], v[142:143], s[98:99] op_sel:[0,1] op_sel_hi:[1,1]
	v_pk_mul_f32 v[138:139], v[138:139], s[100:101] op_sel_hi:[1,0]
	v_pk_mul_f32 v[140:141], v[140:141], s[100:101] op_sel_hi:[1,0]
	v_pk_mul_f32 v[144:145], v[144:145], s[100:101] op_sel_hi:[1,0]
	v_pk_mul_f32 v[142:143], v[142:143], s[100:101] op_sel_hi:[1,0]
	v_exp_f32_e32 v138, v138
	v_exp_f32_e32 v139, v139
	v_exp_f32_e32 v140, v140
	v_exp_f32_e32 v141, v141
	v_exp_f32_e32 v144, v144
	v_exp_f32_e32 v145, v145
	v_exp_f32_e32 v142, v142
	v_exp_f32_e32 v143, v143
	v_pk_add_f32 v[138:139], v[138:139], s[100:101] op_sel:[0,1] op_sel_hi:[1,1]
	v_pk_add_f32 v[140:141], v[140:141], s[100:101] op_sel:[0,1] op_sel_hi:[1,1]
	v_pk_add_f32 v[144:145], v[144:145], s[100:101] op_sel:[0,1] op_sel_hi:[1,1]
	v_pk_add_f32 v[142:143], v[142:143], s[100:101] op_sel:[0,1] op_sel_hi:[1,1]
	v_rcp_f32_e32 v138, v138
	v_rcp_f32_e32 v139, v139
	v_rcp_f32_e32 v140, v140
	v_rcp_f32_e32 v141, v141
	v_rcp_f32_e32 v144, v144
	v_rcp_f32_e32 v145, v145
	v_rcp_f32_e32 v142, v142
	v_rcp_f32_e32 v143, v143
	v_pk_mul_f32 v[138:139], v[134:135], v[138:139]
	v_pk_mul_f32 v[140:141], v[136:137], v[140:141]
	v_pk_mul_f32 v[144:145], v[132:133], v[144:145]
	v_pk_mul_f32 v[142:143], v[130:131], v[142:143]

.LBB0_353:
	s_andn2_b64 vcc, exec, s[14:15]
	s_cbranch_vccnz .LBB0_357
	s_cmp_eq_u32 s16, 1
	s_cbranch_scc0 .LBB0_356
	s_mov_b32 s100, 0xbfb8aa3b
	s_mov_b32 s101, 1.0
	v_pk_mul_f32 v[138:139], v[134:135], s[100:101] op_sel_hi:[1,0]
	v_pk_mul_f32 v[140:141], v[130:131], s[100:101] op_sel_hi:[1,0]
	v_pk_mul_f32 v[142:143], v[136:137], s[100:101] op_sel_hi:[1,0]
	v_pk_mul_f32 v[144:145], v[132:133], s[100:101] op_sel_hi:[1,0]
	v_exp_f32_e32 v138, v138
	v_exp_f32_e32 v139, v139
	v_exp_f32_e32 v140, v140
	v_exp_f32_e32 v141, v141
	v_exp_f32_e32 v142, v142
	v_exp_f32_e32 v143, v143
	v_exp_f32_e32 v144, v144
	v_exp_f32_e32 v145, v145
	v_pk_add_f32 v[138:139], v[138:139], s[100:101] op_sel:[0,1] op_sel_hi:[1,1]
	v_pk_add_f32 v[140:141], v[140:141], s[100:101] op_sel:[0,1] op_sel_hi:[1,1]
	v_pk_add_f32 v[142:143], v[142:143], s[100:101] op_sel:[0,1] op_sel_hi:[1,1]
	v_pk_add_f32 v[144:145], v[144:145], s[100:101] op_sel:[0,1] op_sel_hi:[1,1]
	v_rcp_f32_e32 v138, v138
	v_rcp_f32_e32 v139, v139
	v_rcp_f32_e32 v140, v140
	v_rcp_f32_e32 v141, v141
	v_rcp_f32_e32 v142, v142
	v_rcp_f32_e32 v143, v143
	v_rcp_f32_e32 v144, v144
	v_rcp_f32_e32 v145, v145
	v_pk_mul_f32 v[134:135], v[134:135], v[138:139]
	v_pk_mul_f32 v[130:131], v[130:131], v[140:141]
	v_pk_mul_f32 v[136:137], v[136:137], v[142:143]
	v_pk_mul_f32 v[132:133], v[132:133], v[144:145]

.LBB0_357:
	v_cvt_pk_bf16_f32 v130, v138, v139
	v_cvt_pk_bf16_f32 v131, v140, v141
	v_cvt_pk_bf16_f32 v132, v142, v143
	v_cvt_pk_bf16_f32 v133, v144, v145
	global_store_dwordx4 v[180:181], v[130:133], off offset:256 nt
	s_cmp_lt_i32 s16, 2
	s_mov_b64 s[14:15], -1
	v_fmamk_f32 v130, v168, 0x3a800000, v235
	v_rsq_f32_e32 v138, v130
	s_nop 0
	v_pk_fma_f32 v[128:129], v[138:139], v[128:129], v[72:73] op_sel_hi:[0,1,1]
	v_pk_fma_f32 v[126:127], v[138:139], v[126:127], v[70:71] op_sel_hi:[0,1,1]
	v_pk_fma_f32 v[124:125], v[138:139], v[124:125], v[68:69] op_sel_hi:[0,1,1]
	v_pk_fma_f32 v[122:123], v[138:139], v[122:123], v[66:67] op_sel_hi:[0,1,1]
	s_cbranch_scc1 .LBB0_361
	v_mov_b64_e32 v[136:137], v[124:125]
	v_mov_b64_e32 v[132:133], v[128:129]
	s_cmp_eq_u32 s16, 2
	v_mov_b64_e32 v[134:135], v[122:123]
	v_mov_b64_e32 v[130:131], v[126:127]
	s_cbranch_scc0 .LBB0_360
	s_mov_b32 s98, 0x3d372713
	s_mov_b32 s99, 0x3fcc422a
	s_mov_b32 s100, 0xbfb8aa3b
	s_mov_b32 s101, 1.0
	v_pk_mul_f32 v[130:131], v[126:127], s[98:99] op_sel_hi:[1,0]
	v_pk_mul_f32 v[132:133], v[128:129], s[98:99] op_sel_hi:[1,0]
	v_pk_mul_f32 v[136:137], v[124:125], s[98:99] op_sel_hi:[1,0]
	v_pk_mul_f32 v[134:135], v[122:123], s[98:99] op_sel_hi:[1,0]
	v_pk_mul_f32 v[130:131], v[126:127], v[130:131]
	v_pk_mul_f32 v[132:133], v[128:129], v[132:133]
	v_pk_mul_f32 v[136:137], v[124:125], v[136:137]
	v_pk_mul_f32 v[134:135], v[122:123], v[134:135]
	v_pk_fma_f32 v[130:131], v[126:127], v[130:131], v[126:127]
	v_pk_fma_f32 v[132:133], v[128:129], v[132:133], v[128:129]
	v_pk_fma_f32 v[136:137], v[124:125], v[136:137], v[124:125]
	v_pk_fma_f32 v[134:135], v[122:123], v[134:135], v[122:123]
	v_pk_mul_f32 v[130:131], v[130:131], s[98:99] op_sel:[0,1] op_sel_hi:[1,1]
	v_pk_mul_f32 v[132:133], v[132:133], s[98:99] op_sel:[0,1] op_sel_hi:[1,1]
	v_pk_mul_f32 v[136:137], v[136:137], s[98:99] op_sel:[0,1] op_sel_hi:[1,1]
	v_pk_mul_f32 v[134:135], v[134:135], s[98:99] op_sel:[0,1] op_sel_hi:[1,1]
	v_pk_mul_f32 v[130:131], v[130:131], s[100:101] op_sel_hi:[1,0]
	v_pk_mul_f32 v[132:133], v[132:133], s[100:101] op_sel_hi:[1,0]
	v_pk_mul_f32 v[136:137], v[136:137], s[100:101] op_sel_hi:[1,0]
	v_pk_mul_f32 v[134:135], v[134:135], s[100:101] op_sel_hi:[1,0]
	v_exp_f32_e32 v130, v130
	v_exp_f32_e32 v131, v131
	v_exp_f32_e32 v132, v132
	v_exp_f32_e32 v133, v133
	v_exp_f32_e32 v136, v136
	v_exp_f32_e32 v137, v137
	v_exp_f32_e32 v134, v134
	v_exp_f32_e32 v135, v135
	v_pk_add_f32 v[130:131], v[130:131], s[100:101] op_sel:[0,1] op_sel_hi:[1,1]
	v_pk_add_f32 v[132:133], v[132:133], s[100:101] op_sel:[0,1] op_sel_hi:[1,1]
	v_pk_add_f32 v[136:137], v[136:137], s[100:101] op_sel:[0,1] op_sel_hi:[1,1]
	v_pk_add_f32 v[134:135], v[134:135], s[100:101] op_sel:[0,1] op_sel_hi:[1,1]
	v_rcp_f32_e32 v130, v130
	v_rcp_f32_e32 v131, v131
	v_rcp_f32_e32 v132, v132
	v_rcp_f32_e32 v133, v133
	v_rcp_f32_e32 v136, v136
	v_rcp_f32_e32 v137, v137
	v_rcp_f32_e32 v134, v134
	v_rcp_f32_e32 v135, v135
	v_pk_mul_f32 v[130:131], v[126:127], v[130:131]
	v_pk_mul_f32 v[132:133], v[128:129], v[132:133]
	v_pk_mul_f32 v[136:137], v[124:125], v[136:137]
	v_pk_mul_f32 v[134:135], v[122:123], v[134:135]

.LBB0_361:
	s_andn2_b64 vcc, exec, s[14:15]
	s_cbranch_vccnz .LBB0_365
	s_cmp_eq_u32 s16, 1
	s_cbranch_scc0 .LBB0_364
	s_mov_b32 s100, 0xbfb8aa3b
	s_mov_b32 s101, 1.0
	v_pk_mul_f32 v[130:131], v[126:127], s[100:101] op_sel_hi:[1,0]
	v_pk_mul_f32 v[132:133], v[122:123], s[100:101] op_sel_hi:[1,0]
	v_pk_mul_f32 v[134:135], v[128:129], s[100:101] op_sel_hi:[1,0]
	v_pk_mul_f32 v[136:137], v[124:125], s[100:101] op_sel_hi:[1,0]
	v_exp_f32_e32 v130, v130
	v_exp_f32_e32 v131, v131
	v_exp_f32_e32 v132, v132
	v_exp_f32_e32 v133, v133
	v_exp_f32_e32 v134, v134
	v_exp_f32_e32 v135, v135
	v_exp_f32_e32 v136, v136
	v_exp_f32_e32 v137, v137
	v_pk_add_f32 v[130:131], v[130:131], s[100:101] op_sel:[0,1] op_sel_hi:[1,1]
	v_pk_add_f32 v[132:133], v[132:133], s[100:101] op_sel:[0,1] op_sel_hi:[1,1]
	v_pk_add_f32 v[134:135], v[134:135], s[100:101] op_sel:[0,1] op_sel_hi:[1,1]
	v_pk_add_f32 v[136:137], v[136:137], s[100:101] op_sel:[0,1] op_sel_hi:[1,1]
	v_rcp_f32_e32 v130, v130
	v_rcp_f32_e32 v131, v131
	v_rcp_f32_e32 v132, v132
	v_rcp_f32_e32 v133, v133
	v_rcp_f32_e32 v134, v134
	v_rcp_f32_e32 v135, v135
	v_rcp_f32_e32 v136, v136
	v_rcp_f32_e32 v137, v137
	v_pk_mul_f32 v[126:127], v[126:127], v[130:131]
	v_pk_mul_f32 v[122:123], v[122:123], v[132:133]
	v_pk_mul_f32 v[128:129], v[128:129], v[134:135]
	v_pk_mul_f32 v[124:125], v[124:125], v[136:137]

.LBB0_365:
	v_or_b32_e32 v124, 16, v172
	v_mov_b64_e32 v[122:123], s[68:69]
	v_mad_i64_i32 v[122:123], s[0:1], v124, s9, v[122:123]
	v_lshl_add_u64 v[140:141], v[174:175], 1, v[122:123]
	v_cvt_pk_bf16_f32 v122, v130, v131
	v_cvt_pk_bf16_f32 v123, v132, v133
	v_cvt_pk_bf16_f32 v124, v134, v135
	v_cvt_pk_bf16_f32 v125, v136, v137
	global_store_dwordx4 v[140:141], v[122:125], off nt
	v_mov_b32_e32 v139, v138
	v_pk_fma_f32 v[118:119], v[138:139], v[118:119], v[54:55]
	v_mov_b32_e32 v122, v138
	v_mov_b32_e32 v123, v138
	v_pk_fma_f32 v[120:121], v[122:123], v[120:121], v[56:57]
	v_pk_fma_f32 v[116:117], v[122:123], v[116:117], v[52:53]
	v_pk_fma_f32 v[114:115], v[138:139], v[114:115], v[50:51]
	s_cmp_lt_i32 s16, 2
	s_mov_b64 s[14:15], -1
	s_cbranch_scc1 .LBB0_369
	v_mov_b64_e32 v[128:129], v[116:117]
	v_mov_b64_e32 v[124:125], v[120:121]
	s_cmp_eq_u32 s16, 2
	v_mov_b64_e32 v[126:127], v[114:115]
	v_mov_b64_e32 v[122:123], v[118:119]
	s_cbranch_scc0 .LBB0_368
	s_mov_b32 s98, 0x3d372713
	s_mov_b32 s99, 0x3fcc422a
	s_mov_b32 s100, 0xbfb8aa3b
	s_mov_b32 s101, 1.0
	v_pk_mul_f32 v[122:123], v[118:119], s[98:99] op_sel_hi:[1,0]
	v_pk_mul_f32 v[124:125], v[120:121], s[98:99] op_sel_hi:[1,0]
	v_pk_mul_f32 v[128:129], v[116:117], s[98:99] op_sel_hi:[1,0]
	v_pk_mul_f32 v[126:127], v[114:115], s[98:99] op_sel_hi:[1,0]
	v_pk_mul_f32 v[122:123], v[118:119], v[122:123]
	v_pk_mul_f32 v[124:125], v[120:121], v[124:125]
	v_pk_mul_f32 v[128:129], v[116:117], v[128:129]
	v_pk_mul_f32 v[126:127], v[114:115], v[126:127]
	v_pk_fma_f32 v[122:123], v[118:119], v[122:123], v[118:119]
	v_pk_fma_f32 v[124:125], v[120:121], v[124:125], v[120:121]
	v_pk_fma_f32 v[128:129], v[116:117], v[128:129], v[116:117]
	v_pk_fma_f32 v[126:127], v[114:115], v[126:127], v[114:115]
	v_pk_mul_f32 v[122:123], v[122:123], s[98:99] op_sel:[0,1] op_sel_hi:[1,1]
	v_pk_mul_f32 v[124:125], v[124:125], s[98:99] op_sel:[0,1] op_sel_hi:[1,1]
	v_pk_mul_f32 v[128:129], v[128:129], s[98:99] op_sel:[0,1] op_sel_hi:[1,1]
	v_pk_mul_f32 v[126:127], v[126:127], s[98:99] op_sel:[0,1] op_sel_hi:[1,1]
	v_pk_mul_f32 v[122:123], v[122:123], s[100:101] op_sel_hi:[1,0]
	v_pk_mul_f32 v[124:125], v[124:125], s[100:101] op_sel_hi:[1,0]
	v_pk_mul_f32 v[128:129], v[128:129], s[100:101] op_sel_hi:[1,0]
	v_pk_mul_f32 v[126:127], v[126:127], s[100:101] op_sel_hi:[1,0]
	v_exp_f32_e32 v122, v122
	v_exp_f32_e32 v123, v123
	v_exp_f32_e32 v124, v124
	v_exp_f32_e32 v125, v125
	v_exp_f32_e32 v128, v128
	v_exp_f32_e32 v129, v129
	v_exp_f32_e32 v126, v126
	v_exp_f32_e32 v127, v127
	v_pk_add_f32 v[122:123], v[122:123], s[100:101] op_sel:[0,1] op_sel_hi:[1,1]
	v_pk_add_f32 v[124:125], v[124:125], s[100:101] op_sel:[0,1] op_sel_hi:[1,1]
	v_pk_add_f32 v[128:129], v[128:129], s[100:101] op_sel:[0,1] op_sel_hi:[1,1]
	v_pk_add_f32 v[126:127], v[126:127], s[100:101] op_sel:[0,1] op_sel_hi:[1,1]
	v_rcp_f32_e32 v122, v122
	v_rcp_f32_e32 v123, v123
	v_rcp_f32_e32 v124, v124
	v_rcp_f32_e32 v125, v125
	v_rcp_f32_e32 v128, v128
	v_rcp_f32_e32 v129, v129
	v_rcp_f32_e32 v126, v126
	v_rcp_f32_e32 v127, v127
	v_pk_mul_f32 v[122:123], v[118:119], v[122:123]
	v_pk_mul_f32 v[124:125], v[120:121], v[124:125]
	v_pk_mul_f32 v[128:129], v[116:117], v[128:129]
	v_pk_mul_f32 v[126:127], v[114:115], v[126:127]

.LBB0_369:
	s_andn2_b64 vcc, exec, s[14:15]
	s_cbranch_vccnz .LBB0_373
	s_cmp_eq_u32 s16, 1
	s_cbranch_scc0 .LBB0_372
	s_mov_b32 s100, 0xbfb8aa3b
	s_mov_b32 s101, 1.0
	v_pk_mul_f32 v[122:123], v[118:119], s[100:101] op_sel_hi:[1,0]
	v_pk_mul_f32 v[124:125], v[114:115], s[100:101] op_sel_hi:[1,0]
	v_pk_mul_f32 v[126:127], v[120:121], s[100:101] op_sel_hi:[1,0]
	v_pk_mul_f32 v[128:129], v[116:117], s[100:101] op_sel_hi:[1,0]
	v_exp_f32_e32 v122, v122
	v_exp_f32_e32 v123, v123
	v_exp_f32_e32 v124, v124
	v_exp_f32_e32 v125, v125
	v_exp_f32_e32 v126, v126
	v_exp_f32_e32 v127, v127
	v_exp_f32_e32 v128, v128
	v_exp_f32_e32 v129, v129
	v_pk_add_f32 v[122:123], v[122:123], s[100:101] op_sel:[0,1] op_sel_hi:[1,1]
	v_pk_add_f32 v[124:125], v[124:125], s[100:101] op_sel:[0,1] op_sel_hi:[1,1]
	v_pk_add_f32 v[126:127], v[126:127], s[100:101] op_sel:[0,1] op_sel_hi:[1,1]
	v_pk_add_f32 v[128:129], v[128:129], s[100:101] op_sel:[0,1] op_sel_hi:[1,1]
	v_rcp_f32_e32 v122, v122
	v_rcp_f32_e32 v123, v123
	v_rcp_f32_e32 v124, v124
	v_rcp_f32_e32 v125, v125
	v_rcp_f32_e32 v126, v126
	v_rcp_f32_e32 v127, v127
	v_rcp_f32_e32 v128, v128
	v_rcp_f32_e32 v129, v129
	v_pk_mul_f32 v[118:119], v[118:119], v[122:123]
	v_pk_mul_f32 v[114:115], v[114:115], v[124:125]
	v_pk_mul_f32 v[120:121], v[120:121], v[126:127]
	v_pk_mul_f32 v[116:117], v[116:117], v[128:129]

.LBB0_373:
	v_cvt_pk_bf16_f32 v114, v122, v123
	v_cvt_pk_bf16_f32 v115, v124, v125
	v_cvt_pk_bf16_f32 v116, v126, v127
	v_cvt_pk_bf16_f32 v117, v128, v129
	global_store_dwordx4 v[140:141], v[114:117], off offset:256 nt
	s_cmp_lt_i32 s16, 2
	s_mov_b64 s[14:15], -1
	v_fmamk_f32 v114, v166, 0x3a800000, v235
	v_rsq_f32_e32 v122, v114
	s_nop 0
	v_pk_fma_f32 v[112:113], v[122:123], v[112:113], v[72:73] op_sel_hi:[0,1,1]
	v_pk_fma_f32 v[110:111], v[122:123], v[110:111], v[70:71] op_sel_hi:[0,1,1]
	v_pk_fma_f32 v[108:109], v[122:123], v[108:109], v[68:69] op_sel_hi:[0,1,1]
	v_pk_fma_f32 v[106:107], v[122:123], v[106:107], v[66:67] op_sel_hi:[0,1,1]
	s_cbranch_scc1 .LBB0_377
	v_mov_b64_e32 v[120:121], v[108:109]
	v_mov_b64_e32 v[116:117], v[112:113]
	s_cmp_eq_u32 s16, 2
	v_mov_b64_e32 v[118:119], v[106:107]
	v_mov_b64_e32 v[114:115], v[110:111]
	s_cbranch_scc0 .LBB0_376
	s_mov_b32 s98, 0x3d372713
	s_mov_b32 s99, 0x3fcc422a
	s_mov_b32 s100, 0xbfb8aa3b
	s_mov_b32 s101, 1.0
	v_pk_mul_f32 v[114:115], v[110:111], s[98:99] op_sel_hi:[1,0]
	v_pk_mul_f32 v[116:117], v[112:113], s[98:99] op_sel_hi:[1,0]
	v_pk_mul_f32 v[120:121], v[108:109], s[98:99] op_sel_hi:[1,0]
	v_pk_mul_f32 v[118:119], v[106:107], s[98:99] op_sel_hi:[1,0]
	v_pk_mul_f32 v[114:115], v[110:111], v[114:115]
	v_pk_mul_f32 v[116:117], v[112:113], v[116:117]
	v_pk_mul_f32 v[120:121], v[108:109], v[120:121]
	v_pk_mul_f32 v[118:119], v[106:107], v[118:119]
	v_pk_fma_f32 v[114:115], v[110:111], v[114:115], v[110:111]
	v_pk_fma_f32 v[116:117], v[112:113], v[116:117], v[112:113]
	v_pk_fma_f32 v[120:121], v[108:109], v[120:121], v[108:109]
	v_pk_fma_f32 v[118:119], v[106:107], v[118:119], v[106:107]
	v_pk_mul_f32 v[114:115], v[114:115], s[98:99] op_sel:[0,1] op_sel_hi:[1,1]
	v_pk_mul_f32 v[116:117], v[116:117], s[98:99] op_sel:[0,1] op_sel_hi:[1,1]
	v_pk_mul_f32 v[120:121], v[120:121], s[98:99] op_sel:[0,1] op_sel_hi:[1,1]
	v_pk_mul_f32 v[118:119], v[118:119], s[98:99] op_sel:[0,1] op_sel_hi:[1,1]
	v_pk_mul_f32 v[114:115], v[114:115], s[100:101] op_sel_hi:[1,0]
	v_pk_mul_f32 v[116:117], v[116:117], s[100:101] op_sel_hi:[1,0]
	v_pk_mul_f32 v[120:121], v[120:121], s[100:101] op_sel_hi:[1,0]
	v_pk_mul_f32 v[118:119], v[118:119], s[100:101] op_sel_hi:[1,0]
	v_exp_f32_e32 v114, v114
	v_exp_f32_e32 v115, v115
	v_exp_f32_e32 v116, v116
	v_exp_f32_e32 v117, v117
	v_exp_f32_e32 v120, v120
	v_exp_f32_e32 v121, v121
	v_exp_f32_e32 v118, v118
	v_exp_f32_e32 v119, v119
	v_pk_add_f32 v[114:115], v[114:115], s[100:101] op_sel:[0,1] op_sel_hi:[1,1]
	v_pk_add_f32 v[116:117], v[116:117], s[100:101] op_sel:[0,1] op_sel_hi:[1,1]
	v_pk_add_f32 v[120:121], v[120:121], s[100:101] op_sel:[0,1] op_sel_hi:[1,1]
	v_pk_add_f32 v[118:119], v[118:119], s[100:101] op_sel:[0,1] op_sel_hi:[1,1]
	v_rcp_f32_e32 v114, v114
	v_rcp_f32_e32 v115, v115
	v_rcp_f32_e32 v116, v116
	v_rcp_f32_e32 v117, v117
	v_rcp_f32_e32 v120, v120
	v_rcp_f32_e32 v121, v121
	v_rcp_f32_e32 v118, v118
	v_rcp_f32_e32 v119, v119
	v_pk_mul_f32 v[114:115], v[110:111], v[114:115]
	v_pk_mul_f32 v[116:117], v[112:113], v[116:117]
	v_pk_mul_f32 v[120:121], v[108:109], v[120:121]
	v_pk_mul_f32 v[118:119], v[106:107], v[118:119]

.LBB0_377:
	s_andn2_b64 vcc, exec, s[14:15]
	s_cbranch_vccnz .LBB0_381
	s_cmp_eq_u32 s16, 1
	s_cbranch_scc0 .LBB0_380
	s_mov_b32 s100, 0xbfb8aa3b
	s_mov_b32 s101, 1.0
	v_pk_mul_f32 v[114:115], v[110:111], s[100:101] op_sel_hi:[1,0]
	v_pk_mul_f32 v[116:117], v[106:107], s[100:101] op_sel_hi:[1,0]
	v_pk_mul_f32 v[118:119], v[112:113], s[100:101] op_sel_hi:[1,0]
	v_pk_mul_f32 v[120:121], v[108:109], s[100:101] op_sel_hi:[1,0]
	v_exp_f32_e32 v114, v114
	v_exp_f32_e32 v115, v115
	v_exp_f32_e32 v116, v116
	v_exp_f32_e32 v117, v117
	v_exp_f32_e32 v118, v118
	v_exp_f32_e32 v119, v119
	v_exp_f32_e32 v120, v120
	v_exp_f32_e32 v121, v121
	v_pk_add_f32 v[114:115], v[114:115], s[100:101] op_sel:[0,1] op_sel_hi:[1,1]
	v_pk_add_f32 v[116:117], v[116:117], s[100:101] op_sel:[0,1] op_sel_hi:[1,1]
	v_pk_add_f32 v[118:119], v[118:119], s[100:101] op_sel:[0,1] op_sel_hi:[1,1]
	v_pk_add_f32 v[120:121], v[120:121], s[100:101] op_sel:[0,1] op_sel_hi:[1,1]
	v_rcp_f32_e32 v114, v114
	v_rcp_f32_e32 v115, v115
	v_rcp_f32_e32 v116, v116
	v_rcp_f32_e32 v117, v117
	v_rcp_f32_e32 v118, v118
	v_rcp_f32_e32 v119, v119
	v_rcp_f32_e32 v120, v120
	v_rcp_f32_e32 v121, v121
	v_pk_mul_f32 v[110:111], v[110:111], v[114:115]
	v_pk_mul_f32 v[106:107], v[106:107], v[116:117]
	v_pk_mul_f32 v[112:113], v[112:113], v[118:119]
	v_pk_mul_f32 v[108:109], v[108:109], v[120:121]

.LBB0_381:
	v_or_b32_e32 v108, 32, v172
	v_mov_b64_e32 v[106:107], s[68:69]
	v_mad_i64_i32 v[106:107], s[0:1], v108, s9, v[106:107]
	v_lshl_add_u64 v[124:125], v[174:175], 1, v[106:107]
	v_cvt_pk_bf16_f32 v106, v114, v115
	v_cvt_pk_bf16_f32 v107, v116, v117
	v_cvt_pk_bf16_f32 v108, v118, v119
	v_cvt_pk_bf16_f32 v109, v120, v121
	global_store_dwordx4 v[124:125], v[106:109], off nt
	v_mov_b32_e32 v123, v122
	v_pk_fma_f32 v[102:103], v[122:123], v[102:103], v[54:55]
	v_mov_b32_e32 v106, v122
	v_mov_b32_e32 v107, v122
	v_pk_fma_f32 v[104:105], v[106:107], v[104:105], v[56:57]
	v_pk_fma_f32 v[100:101], v[106:107], v[100:101], v[52:53]
	v_pk_fma_f32 v[98:99], v[122:123], v[98:99], v[50:51]
	s_cmp_lt_i32 s16, 2
	s_mov_b64 s[14:15], -1
	s_cbranch_scc1 .LBB0_385
	v_mov_b64_e32 v[112:113], v[100:101]
	v_mov_b64_e32 v[108:109], v[104:105]
	s_cmp_eq_u32 s16, 2
	v_mov_b64_e32 v[110:111], v[98:99]
	v_mov_b64_e32 v[106:107], v[102:103]
	s_cbranch_scc0 .LBB0_384
	s_mov_b32 s98, 0x3d372713
	s_mov_b32 s99, 0x3fcc422a
	s_mov_b32 s100, 0xbfb8aa3b
	s_mov_b32 s101, 1.0
	v_pk_mul_f32 v[106:107], v[102:103], s[98:99] op_sel_hi:[1,0]
	v_pk_mul_f32 v[108:109], v[104:105], s[98:99] op_sel_hi:[1,0]
	v_pk_mul_f32 v[112:113], v[100:101], s[98:99] op_sel_hi:[1,0]
	v_pk_mul_f32 v[110:111], v[98:99], s[98:99] op_sel_hi:[1,0]
	v_pk_mul_f32 v[106:107], v[102:103], v[106:107]
	v_pk_mul_f32 v[108:109], v[104:105], v[108:109]
	v_pk_mul_f32 v[112:113], v[100:101], v[112:113]
	v_pk_mul_f32 v[110:111], v[98:99], v[110:111]
	v_pk_fma_f32 v[106:107], v[102:103], v[106:107], v[102:103]
	v_pk_fma_f32 v[108:109], v[104:105], v[108:109], v[104:105]
	v_pk_fma_f32 v[112:113], v[100:101], v[112:113], v[100:101]
	v_pk_fma_f32 v[110:111], v[98:99], v[110:111], v[98:99]
	v_pk_mul_f32 v[106:107], v[106:107], s[98:99] op_sel:[0,1] op_sel_hi:[1,1]
	v_pk_mul_f32 v[108:109], v[108:109], s[98:99] op_sel:[0,1] op_sel_hi:[1,1]
	v_pk_mul_f32 v[112:113], v[112:113], s[98:99] op_sel:[0,1] op_sel_hi:[1,1]
	v_pk_mul_f32 v[110:111], v[110:111], s[98:99] op_sel:[0,1] op_sel_hi:[1,1]
	v_pk_mul_f32 v[106:107], v[106:107], s[100:101] op_sel_hi:[1,0]
	v_pk_mul_f32 v[108:109], v[108:109], s[100:101] op_sel_hi:[1,0]
	v_pk_mul_f32 v[112:113], v[112:113], s[100:101] op_sel_hi:[1,0]
	v_pk_mul_f32 v[110:111], v[110:111], s[100:101] op_sel_hi:[1,0]
	v_exp_f32_e32 v106, v106
	v_exp_f32_e32 v107, v107
	v_exp_f32_e32 v108, v108
	v_exp_f32_e32 v109, v109
	v_exp_f32_e32 v112, v112
	v_exp_f32_e32 v113, v113
	v_exp_f32_e32 v110, v110
	v_exp_f32_e32 v111, v111
	v_pk_add_f32 v[106:107], v[106:107], s[100:101] op_sel:[0,1] op_sel_hi:[1,1]
	v_pk_add_f32 v[108:109], v[108:109], s[100:101] op_sel:[0,1] op_sel_hi:[1,1]
	v_pk_add_f32 v[112:113], v[112:113], s[100:101] op_sel:[0,1] op_sel_hi:[1,1]
	v_pk_add_f32 v[110:111], v[110:111], s[100:101] op_sel:[0,1] op_sel_hi:[1,1]
	v_rcp_f32_e32 v106, v106
	v_rcp_f32_e32 v107, v107
	v_rcp_f32_e32 v108, v108
	v_rcp_f32_e32 v109, v109
	v_rcp_f32_e32 v112, v112
	v_rcp_f32_e32 v113, v113
	v_rcp_f32_e32 v110, v110
	v_rcp_f32_e32 v111, v111
	v_pk_mul_f32 v[106:107], v[102:103], v[106:107]
	v_pk_mul_f32 v[108:109], v[104:105], v[108:109]
	v_pk_mul_f32 v[112:113], v[100:101], v[112:113]
	v_pk_mul_f32 v[110:111], v[98:99], v[110:111]

.LBB0_385:
	s_andn2_b64 vcc, exec, s[14:15]
	s_cbranch_vccnz .LBB0_389
	s_cmp_eq_u32 s16, 1
	s_cbranch_scc0 .LBB0_388
	s_mov_b32 s100, 0xbfb8aa3b
	s_mov_b32 s101, 1.0
	v_pk_mul_f32 v[106:107], v[102:103], s[100:101] op_sel_hi:[1,0]
	v_pk_mul_f32 v[108:109], v[98:99], s[100:101] op_sel_hi:[1,0]
	v_pk_mul_f32 v[110:111], v[104:105], s[100:101] op_sel_hi:[1,0]
	v_pk_mul_f32 v[112:113], v[100:101], s[100:101] op_sel_hi:[1,0]
	v_exp_f32_e32 v106, v106
	v_exp_f32_e32 v107, v107
	v_exp_f32_e32 v108, v108
	v_exp_f32_e32 v109, v109
	v_exp_f32_e32 v110, v110
	v_exp_f32_e32 v111, v111
	v_exp_f32_e32 v112, v112
	v_exp_f32_e32 v113, v113
	v_pk_add_f32 v[106:107], v[106:107], s[100:101] op_sel:[0,1] op_sel_hi:[1,1]
	v_pk_add_f32 v[108:109], v[108:109], s[100:101] op_sel:[0,1] op_sel_hi:[1,1]
	v_pk_add_f32 v[110:111], v[110:111], s[100:101] op_sel:[0,1] op_sel_hi:[1,1]
	v_pk_add_f32 v[112:113], v[112:113], s[100:101] op_sel:[0,1] op_sel_hi:[1,1]
	v_rcp_f32_e32 v106, v106
	v_rcp_f32_e32 v107, v107
	v_rcp_f32_e32 v108, v108
	v_rcp_f32_e32 v109, v109
	v_rcp_f32_e32 v110, v110
	v_rcp_f32_e32 v111, v111
	v_rcp_f32_e32 v112, v112
	v_rcp_f32_e32 v113, v113
	v_pk_mul_f32 v[102:103], v[102:103], v[106:107]
	v_pk_mul_f32 v[98:99], v[98:99], v[108:109]
	v_pk_mul_f32 v[104:105], v[104:105], v[110:111]
	v_pk_mul_f32 v[100:101], v[100:101], v[112:113]

.LBB0_389:
	v_cvt_pk_bf16_f32 v98, v106, v107
	v_cvt_pk_bf16_f32 v99, v108, v109
	v_cvt_pk_bf16_f32 v100, v110, v111
	v_cvt_pk_bf16_f32 v101, v112, v113
	global_store_dwordx4 v[124:125], v[98:101], off offset:256 nt
	s_cmp_lt_i32 s16, 2
	s_mov_b64 s[14:15], -1
	v_fmamk_f32 v98, v164, 0x3a800000, v235
	v_rsq_f32_e32 v106, v98
	s_nop 0
	v_pk_fma_f32 v[96:97], v[106:107], v[96:97], v[72:73] op_sel_hi:[0,1,1]
	v_pk_fma_f32 v[94:95], v[106:107], v[94:95], v[70:71] op_sel_hi:[0,1,1]
	v_pk_fma_f32 v[92:93], v[106:107], v[92:93], v[68:69] op_sel_hi:[0,1,1]
	v_pk_fma_f32 v[90:91], v[106:107], v[90:91], v[66:67] op_sel_hi:[0,1,1]
	s_cbranch_scc1 .LBB0_393
	v_mov_b64_e32 v[104:105], v[92:93]
	v_mov_b64_e32 v[100:101], v[96:97]
	s_cmp_eq_u32 s16, 2
	v_mov_b64_e32 v[102:103], v[90:91]
	v_mov_b64_e32 v[98:99], v[94:95]
	s_cbranch_scc0 .LBB0_392
	s_mov_b32 s98, 0x3d372713
	s_mov_b32 s99, 0x3fcc422a
	s_mov_b32 s100, 0xbfb8aa3b
	s_mov_b32 s101, 1.0
	v_pk_mul_f32 v[98:99], v[94:95], s[98:99] op_sel_hi:[1,0]
	v_pk_mul_f32 v[100:101], v[96:97], s[98:99] op_sel_hi:[1,0]
	v_pk_mul_f32 v[104:105], v[92:93], s[98:99] op_sel_hi:[1,0]
	v_pk_mul_f32 v[102:103], v[90:91], s[98:99] op_sel_hi:[1,0]
	v_pk_mul_f32 v[98:99], v[94:95], v[98:99]
	v_pk_mul_f32 v[100:101], v[96:97], v[100:101]
	v_pk_mul_f32 v[104:105], v[92:93], v[104:105]
	v_pk_mul_f32 v[102:103], v[90:91], v[102:103]
	v_pk_fma_f32 v[98:99], v[94:95], v[98:99], v[94:95]
	v_pk_fma_f32 v[100:101], v[96:97], v[100:101], v[96:97]
	v_pk_fma_f32 v[104:105], v[92:93], v[104:105], v[92:93]
	v_pk_fma_f32 v[102:103], v[90:91], v[102:103], v[90:91]
	v_pk_mul_f32 v[98:99], v[98:99], s[98:99] op_sel:[0,1] op_sel_hi:[1,1]
	v_pk_mul_f32 v[100:101], v[100:101], s[98:99] op_sel:[0,1] op_sel_hi:[1,1]
	v_pk_mul_f32 v[104:105], v[104:105], s[98:99] op_sel:[0,1] op_sel_hi:[1,1]
	v_pk_mul_f32 v[102:103], v[102:103], s[98:99] op_sel:[0,1] op_sel_hi:[1,1]
	v_pk_mul_f32 v[98:99], v[98:99], s[100:101] op_sel_hi:[1,0]
	v_pk_mul_f32 v[100:101], v[100:101], s[100:101] op_sel_hi:[1,0]
	v_pk_mul_f32 v[104:105], v[104:105], s[100:101] op_sel_hi:[1,0]
	v_pk_mul_f32 v[102:103], v[102:103], s[100:101] op_sel_hi:[1,0]
	v_exp_f32_e32 v98, v98
	v_exp_f32_e32 v99, v99
	v_exp_f32_e32 v100, v100
	v_exp_f32_e32 v101, v101
	v_exp_f32_e32 v104, v104
	v_exp_f32_e32 v105, v105
	v_exp_f32_e32 v102, v102
	v_exp_f32_e32 v103, v103
	v_pk_add_f32 v[98:99], v[98:99], s[100:101] op_sel:[0,1] op_sel_hi:[1,1]
	v_pk_add_f32 v[100:101], v[100:101], s[100:101] op_sel:[0,1] op_sel_hi:[1,1]
	v_pk_add_f32 v[104:105], v[104:105], s[100:101] op_sel:[0,1] op_sel_hi:[1,1]
	v_pk_add_f32 v[102:103], v[102:103], s[100:101] op_sel:[0,1] op_sel_hi:[1,1]
	v_rcp_f32_e32 v98, v98
	v_rcp_f32_e32 v99, v99
	v_rcp_f32_e32 v100, v100
	v_rcp_f32_e32 v101, v101
	v_rcp_f32_e32 v104, v104
	v_rcp_f32_e32 v105, v105
	v_rcp_f32_e32 v102, v102
	v_rcp_f32_e32 v103, v103
	v_pk_mul_f32 v[98:99], v[94:95], v[98:99]
	v_pk_mul_f32 v[100:101], v[96:97], v[100:101]
	v_pk_mul_f32 v[104:105], v[92:93], v[104:105]
	v_pk_mul_f32 v[102:103], v[90:91], v[102:103]

.LBB0_393:
	s_andn2_b64 vcc, exec, s[14:15]
	s_cbranch_vccnz .LBB0_397
	s_cmp_eq_u32 s16, 1
	s_cbranch_scc0 .LBB0_396
	s_mov_b32 s100, 0xbfb8aa3b
	s_mov_b32 s101, 1.0
	v_pk_mul_f32 v[98:99], v[94:95], s[100:101] op_sel_hi:[1,0]
	v_pk_mul_f32 v[100:101], v[90:91], s[100:101] op_sel_hi:[1,0]
	v_pk_mul_f32 v[102:103], v[96:97], s[100:101] op_sel_hi:[1,0]
	v_pk_mul_f32 v[104:105], v[92:93], s[100:101] op_sel_hi:[1,0]
	v_exp_f32_e32 v98, v98
	v_exp_f32_e32 v99, v99
	v_exp_f32_e32 v100, v100
	v_exp_f32_e32 v101, v101
	v_exp_f32_e32 v102, v102
	v_exp_f32_e32 v103, v103
	v_exp_f32_e32 v104, v104
	v_exp_f32_e32 v105, v105
	v_pk_add_f32 v[98:99], v[98:99], s[100:101] op_sel:[0,1] op_sel_hi:[1,1]
	v_pk_add_f32 v[100:101], v[100:101], s[100:101] op_sel:[0,1] op_sel_hi:[1,1]
	v_pk_add_f32 v[102:103], v[102:103], s[100:101] op_sel:[0,1] op_sel_hi:[1,1]
	v_pk_add_f32 v[104:105], v[104:105], s[100:101] op_sel:[0,1] op_sel_hi:[1,1]
	v_rcp_f32_e32 v98, v98
	v_rcp_f32_e32 v99, v99
	v_rcp_f32_e32 v100, v100
	v_rcp_f32_e32 v101, v101
	v_rcp_f32_e32 v102, v102
	v_rcp_f32_e32 v103, v103
	v_rcp_f32_e32 v104, v104
	v_rcp_f32_e32 v105, v105
	v_pk_mul_f32 v[94:95], v[94:95], v[98:99]
	v_pk_mul_f32 v[90:91], v[90:91], v[100:101]
	v_pk_mul_f32 v[96:97], v[96:97], v[102:103]
	v_pk_mul_f32 v[92:93], v[92:93], v[104:105]

.LBB0_397:
	v_or_b32_e32 v92, 48, v172
	v_mov_b64_e32 v[90:91], s[68:69]
	v_mad_i64_i32 v[90:91], s[0:1], v92, s9, v[90:91]
	v_lshl_add_u64 v[108:109], v[174:175], 1, v[90:91]
	v_cvt_pk_bf16_f32 v90, v98, v99
	v_cvt_pk_bf16_f32 v91, v100, v101
	v_cvt_pk_bf16_f32 v92, v102, v103
	v_cvt_pk_bf16_f32 v93, v104, v105
	global_store_dwordx4 v[108:109], v[90:93], off nt
	v_mov_b32_e32 v107, v106
	v_pk_fma_f32 v[86:87], v[106:107], v[86:87], v[54:55]
	v_mov_b32_e32 v90, v106
	v_mov_b32_e32 v91, v106
	v_pk_fma_f32 v[88:89], v[90:91], v[88:89], v[56:57]
	v_pk_fma_f32 v[84:85], v[90:91], v[84:85], v[52:53]
	v_pk_fma_f32 v[82:83], v[106:107], v[82:83], v[50:51]
	s_cmp_lt_i32 s16, 2
	s_mov_b64 s[14:15], -1
	s_cbranch_scc1 .LBB0_401
	v_mov_b64_e32 v[96:97], v[84:85]
	v_mov_b64_e32 v[92:93], v[88:89]
	s_cmp_eq_u32 s16, 2
	v_mov_b64_e32 v[94:95], v[82:83]
	v_mov_b64_e32 v[90:91], v[86:87]
	s_cbranch_scc0 .LBB0_400
	s_mov_b32 s98, 0x3d372713
	s_mov_b32 s99, 0x3fcc422a
	s_mov_b32 s100, 0xbfb8aa3b
	s_mov_b32 s101, 1.0
	v_pk_mul_f32 v[90:91], v[86:87], s[98:99] op_sel_hi:[1,0]
	v_pk_mul_f32 v[92:93], v[88:89], s[98:99] op_sel_hi:[1,0]
	v_pk_mul_f32 v[96:97], v[84:85], s[98:99] op_sel_hi:[1,0]
	v_pk_mul_f32 v[94:95], v[82:83], s[98:99] op_sel_hi:[1,0]
	v_pk_mul_f32 v[90:91], v[86:87], v[90:91]
	v_pk_mul_f32 v[92:93], v[88:89], v[92:93]
	v_pk_mul_f32 v[96:97], v[84:85], v[96:97]
	v_pk_mul_f32 v[94:95], v[82:83], v[94:95]
	v_pk_fma_f32 v[90:91], v[86:87], v[90:91], v[86:87]
	v_pk_fma_f32 v[92:93], v[88:89], v[92:93], v[88:89]
	v_pk_fma_f32 v[96:97], v[84:85], v[96:97], v[84:85]
	v_pk_fma_f32 v[94:95], v[82:83], v[94:95], v[82:83]
	v_pk_mul_f32 v[90:91], v[90:91], s[98:99] op_sel:[0,1] op_sel_hi:[1,1]
	v_pk_mul_f32 v[92:93], v[92:93], s[98:99] op_sel:[0,1] op_sel_hi:[1,1]
	v_pk_mul_f32 v[96:97], v[96:97], s[98:99] op_sel:[0,1] op_sel_hi:[1,1]
	v_pk_mul_f32 v[94:95], v[94:95], s[98:99] op_sel:[0,1] op_sel_hi:[1,1]
	v_pk_mul_f32 v[90:91], v[90:91], s[100:101] op_sel_hi:[1,0]
	v_pk_mul_f32 v[92:93], v[92:93], s[100:101] op_sel_hi:[1,0]
	v_pk_mul_f32 v[96:97], v[96:97], s[100:101] op_sel_hi:[1,0]
	v_pk_mul_f32 v[94:95], v[94:95], s[100:101] op_sel_hi:[1,0]
	v_exp_f32_e32 v90, v90
	v_exp_f32_e32 v91, v91
	v_exp_f32_e32 v92, v92
	v_exp_f32_e32 v93, v93
	v_exp_f32_e32 v96, v96
	v_exp_f32_e32 v97, v97
	v_exp_f32_e32 v94, v94
	v_exp_f32_e32 v95, v95
	v_pk_add_f32 v[90:91], v[90:91], s[100:101] op_sel:[0,1] op_sel_hi:[1,1]
	v_pk_add_f32 v[92:93], v[92:93], s[100:101] op_sel:[0,1] op_sel_hi:[1,1]
	v_pk_add_f32 v[96:97], v[96:97], s[100:101] op_sel:[0,1] op_sel_hi:[1,1]
	v_pk_add_f32 v[94:95], v[94:95], s[100:101] op_sel:[0,1] op_sel_hi:[1,1]
	v_rcp_f32_e32 v90, v90
	v_rcp_f32_e32 v91, v91
	v_rcp_f32_e32 v92, v92
	v_rcp_f32_e32 v93, v93
	v_rcp_f32_e32 v96, v96
	v_rcp_f32_e32 v97, v97
	v_rcp_f32_e32 v94, v94
	v_rcp_f32_e32 v95, v95
	v_pk_mul_f32 v[90:91], v[86:87], v[90:91]
	v_pk_mul_f32 v[92:93], v[88:89], v[92:93]
	v_pk_mul_f32 v[96:97], v[84:85], v[96:97]
	v_pk_mul_f32 v[94:95], v[82:83], v[94:95]

.LBB0_401:
	s_andn2_b64 vcc, exec, s[14:15]
	s_cbranch_vccnz .LBB0_405
	s_cmp_eq_u32 s16, 1
	s_cbranch_scc0 .LBB0_404
	s_mov_b32 s100, 0xbfb8aa3b
	s_mov_b32 s101, 1.0
	v_pk_mul_f32 v[90:91], v[86:87], s[100:101] op_sel_hi:[1,0]
	v_pk_mul_f32 v[92:93], v[82:83], s[100:101] op_sel_hi:[1,0]
	v_pk_mul_f32 v[94:95], v[88:89], s[100:101] op_sel_hi:[1,0]
	v_pk_mul_f32 v[96:97], v[84:85], s[100:101] op_sel_hi:[1,0]
	v_exp_f32_e32 v90, v90
	v_exp_f32_e32 v91, v91
	v_exp_f32_e32 v92, v92
	v_exp_f32_e32 v93, v93
	v_exp_f32_e32 v94, v94
	v_exp_f32_e32 v95, v95
	v_exp_f32_e32 v96, v96
	v_exp_f32_e32 v97, v97
	v_pk_add_f32 v[90:91], v[90:91], s[100:101] op_sel:[0,1] op_sel_hi:[1,1]
	v_pk_add_f32 v[92:93], v[92:93], s[100:101] op_sel:[0,1] op_sel_hi:[1,1]
	v_pk_add_f32 v[94:95], v[94:95], s[100:101] op_sel:[0,1] op_sel_hi:[1,1]
	v_pk_add_f32 v[96:97], v[96:97], s[100:101] op_sel:[0,1] op_sel_hi:[1,1]
	v_rcp_f32_e32 v90, v90
	v_rcp_f32_e32 v91, v91
	v_rcp_f32_e32 v92, v92
	v_rcp_f32_e32 v93, v93
	v_rcp_f32_e32 v94, v94
	v_rcp_f32_e32 v95, v95
	v_rcp_f32_e32 v96, v96
	v_rcp_f32_e32 v97, v97
	v_pk_mul_f32 v[86:87], v[86:87], v[90:91]
	v_pk_mul_f32 v[82:83], v[82:83], v[92:93]
	v_pk_mul_f32 v[88:89], v[88:89], v[94:95]
	v_pk_mul_f32 v[84:85], v[84:85], v[96:97]

.LBB0_405:
	v_cvt_pk_bf16_f32 v82, v90, v91
	v_cvt_pk_bf16_f32 v83, v92, v93
	v_cvt_pk_bf16_f32 v84, v94, v95
	v_cvt_pk_bf16_f32 v85, v96, v97
	global_store_dwordx4 v[108:109], v[82:85], off offset:256 nt
	s_cmp_lt_i32 s16, 2
	s_mov_b64 s[14:15], -1
	v_fmamk_f32 v82, v171, 0x3a800000, v235
	v_rsq_f32_e32 v90, v82
	s_nop 0
	v_pk_fma_f32 v[80:81], v[80:81], v[90:91], v[72:73] op_sel_hi:[1,0,1]
	v_pk_fma_f32 v[78:79], v[78:79], v[90:91], v[70:71] op_sel_hi:[1,0,1]
	v_pk_fma_f32 v[76:77], v[76:77], v[90:91], v[68:69] op_sel_hi:[1,0,1]
	v_pk_fma_f32 v[74:75], v[74:75], v[90:91], v[66:67] op_sel_hi:[1,0,1]
	s_cbranch_scc1 .LBB0_409
	v_mov_b64_e32 v[88:89], v[76:77]
	v_mov_b64_e32 v[84:85], v[80:81]
	s_cmp_eq_u32 s16, 2
	v_mov_b64_e32 v[86:87], v[74:75]
	v_mov_b64_e32 v[82:83], v[78:79]
	s_cbranch_scc0 .LBB0_408
	s_mov_b32 s98, 0x3d372713
	s_mov_b32 s99, 0x3fcc422a
	s_mov_b32 s100, 0xbfb8aa3b
	s_mov_b32 s101, 1.0
	v_pk_mul_f32 v[82:83], v[78:79], s[98:99] op_sel_hi:[1,0]
	v_pk_mul_f32 v[84:85], v[80:81], s[98:99] op_sel_hi:[1,0]
	v_pk_mul_f32 v[88:89], v[76:77], s[98:99] op_sel_hi:[1,0]
	v_pk_mul_f32 v[86:87], v[74:75], s[98:99] op_sel_hi:[1,0]
	v_pk_mul_f32 v[82:83], v[78:79], v[82:83]
	v_pk_mul_f32 v[84:85], v[80:81], v[84:85]
	v_pk_mul_f32 v[88:89], v[76:77], v[88:89]
	v_pk_mul_f32 v[86:87], v[74:75], v[86:87]
	v_pk_fma_f32 v[82:83], v[78:79], v[82:83], v[78:79]
	v_pk_fma_f32 v[84:85], v[80:81], v[84:85], v[80:81]
	v_pk_fma_f32 v[88:89], v[76:77], v[88:89], v[76:77]
	v_pk_fma_f32 v[86:87], v[74:75], v[86:87], v[74:75]
	v_pk_mul_f32 v[82:83], v[82:83], s[98:99] op_sel:[0,1] op_sel_hi:[1,1]
	v_pk_mul_f32 v[84:85], v[84:85], s[98:99] op_sel:[0,1] op_sel_hi:[1,1]
	v_pk_mul_f32 v[88:89], v[88:89], s[98:99] op_sel:[0,1] op_sel_hi:[1,1]
	v_pk_mul_f32 v[86:87], v[86:87], s[98:99] op_sel:[0,1] op_sel_hi:[1,1]
	v_pk_mul_f32 v[82:83], v[82:83], s[100:101] op_sel_hi:[1,0]
	v_pk_mul_f32 v[84:85], v[84:85], s[100:101] op_sel_hi:[1,0]
	v_pk_mul_f32 v[88:89], v[88:89], s[100:101] op_sel_hi:[1,0]
	v_pk_mul_f32 v[86:87], v[86:87], s[100:101] op_sel_hi:[1,0]
	v_exp_f32_e32 v82, v82
	v_exp_f32_e32 v83, v83
	v_exp_f32_e32 v84, v84
	v_exp_f32_e32 v85, v85
	v_exp_f32_e32 v88, v88
	v_exp_f32_e32 v89, v89
	v_exp_f32_e32 v86, v86
	v_exp_f32_e32 v87, v87
	v_pk_add_f32 v[82:83], v[82:83], s[100:101] op_sel:[0,1] op_sel_hi:[1,1]
	v_pk_add_f32 v[84:85], v[84:85], s[100:101] op_sel:[0,1] op_sel_hi:[1,1]
	v_pk_add_f32 v[88:89], v[88:89], s[100:101] op_sel:[0,1] op_sel_hi:[1,1]
	v_pk_add_f32 v[86:87], v[86:87], s[100:101] op_sel:[0,1] op_sel_hi:[1,1]
	v_rcp_f32_e32 v82, v82
	v_rcp_f32_e32 v83, v83
	v_rcp_f32_e32 v84, v84
	v_rcp_f32_e32 v85, v85
	v_rcp_f32_e32 v88, v88
	v_rcp_f32_e32 v89, v89
	v_rcp_f32_e32 v86, v86
	v_rcp_f32_e32 v87, v87
	v_pk_mul_f32 v[82:83], v[78:79], v[82:83]
	v_pk_mul_f32 v[84:85], v[80:81], v[84:85]
	v_pk_mul_f32 v[88:89], v[76:77], v[88:89]
	v_pk_mul_f32 v[86:87], v[74:75], v[86:87]

.LBB0_409:
	s_andn2_b64 vcc, exec, s[14:15]
	s_cbranch_vccnz .LBB0_413
	s_cmp_eq_u32 s16, 1
	s_cbranch_scc0 .LBB0_412
	s_mov_b32 s100, 0xbfb8aa3b
	s_mov_b32 s101, 1.0
	v_pk_mul_f32 v[82:83], v[78:79], s[100:101] op_sel_hi:[1,0]
	v_pk_mul_f32 v[84:85], v[74:75], s[100:101] op_sel_hi:[1,0]
	v_pk_mul_f32 v[86:87], v[80:81], s[100:101] op_sel_hi:[1,0]
	v_pk_mul_f32 v[88:89], v[76:77], s[100:101] op_sel_hi:[1,0]
	v_exp_f32_e32 v82, v82
	v_exp_f32_e32 v83, v83
	v_exp_f32_e32 v84, v84
	v_exp_f32_e32 v85, v85
	v_exp_f32_e32 v86, v86
	v_exp_f32_e32 v87, v87
	v_exp_f32_e32 v88, v88
	v_exp_f32_e32 v89, v89
	v_pk_add_f32 v[82:83], v[82:83], s[100:101] op_sel:[0,1] op_sel_hi:[1,1]
	v_pk_add_f32 v[84:85], v[84:85], s[100:101] op_sel:[0,1] op_sel_hi:[1,1]
	v_pk_add_f32 v[86:87], v[86:87], s[100:101] op_sel:[0,1] op_sel_hi:[1,1]
	v_pk_add_f32 v[88:89], v[88:89], s[100:101] op_sel:[0,1] op_sel_hi:[1,1]
	v_rcp_f32_e32 v82, v82
	v_rcp_f32_e32 v83, v83
	v_rcp_f32_e32 v84, v84
	v_rcp_f32_e32 v85, v85
	v_rcp_f32_e32 v86, v86
	v_rcp_f32_e32 v87, v87
	v_rcp_f32_e32 v88, v88
	v_rcp_f32_e32 v89, v89
	v_pk_mul_f32 v[78:79], v[78:79], v[82:83]
	v_pk_mul_f32 v[74:75], v[74:75], v[84:85]
	v_pk_mul_f32 v[80:81], v[80:81], v[86:87]
	v_pk_mul_f32 v[76:77], v[76:77], v[88:89]

.LBB0_413:
	v_mov_b64_e32 v[74:75], s[68:69]
	v_mad_i64_i32 v[74:75], s[0:1], v176, s9, v[74:75]
	v_lshl_add_u64 v[92:93], v[174:175], 1, v[74:75]
	v_cvt_pk_bf16_f32 v74, v82, v83
	v_cvt_pk_bf16_f32 v75, v84, v85
	v_cvt_pk_bf16_f32 v76, v86, v87
	v_cvt_pk_bf16_f32 v77, v88, v89
	global_store_dwordx4 v[92:93], v[74:77], off nt
	v_mov_b32_e32 v91, v90
	v_pk_fma_f32 v[62:63], v[62:63], v[90:91], v[54:55]
	v_mov_b32_e32 v74, v90
	v_mov_b32_e32 v75, v90
	v_pk_fma_f32 v[64:65], v[64:65], v[74:75], v[56:57]
	v_pk_fma_f32 v[60:61], v[60:61], v[74:75], v[52:53]
	v_pk_fma_f32 v[58:59], v[58:59], v[90:91], v[50:51]
	s_cmp_lt_i32 s16, 2
	s_mov_b64 s[14:15], -1
	s_cbranch_scc1 .LBB0_417
	v_mov_b64_e32 v[80:81], v[60:61]
	v_mov_b64_e32 v[76:77], v[64:65]
	s_cmp_eq_u32 s16, 2
	v_mov_b64_e32 v[78:79], v[58:59]
	v_mov_b64_e32 v[74:75], v[62:63]
	s_cbranch_scc0 .LBB0_416
	s_mov_b32 s98, 0x3d372713
	s_mov_b32 s99, 0x3fcc422a
	s_mov_b32 s100, 0xbfb8aa3b
	s_mov_b32 s101, 1.0
	v_pk_mul_f32 v[74:75], v[62:63], s[98:99] op_sel_hi:[1,0]
	v_pk_mul_f32 v[76:77], v[64:65], s[98:99] op_sel_hi:[1,0]
	v_pk_mul_f32 v[80:81], v[60:61], s[98:99] op_sel_hi:[1,0]
	v_pk_mul_f32 v[78:79], v[58:59], s[98:99] op_sel_hi:[1,0]
	v_pk_mul_f32 v[74:75], v[62:63], v[74:75]
	v_pk_mul_f32 v[76:77], v[64:65], v[76:77]
	v_pk_mul_f32 v[80:81], v[60:61], v[80:81]
	v_pk_mul_f32 v[78:79], v[58:59], v[78:79]
	v_pk_fma_f32 v[74:75], v[62:63], v[74:75], v[62:63]
	v_pk_fma_f32 v[76:77], v[64:65], v[76:77], v[64:65]
	v_pk_fma_f32 v[80:81], v[60:61], v[80:81], v[60:61]
	v_pk_fma_f32 v[78:79], v[58:59], v[78:79], v[58:59]
	v_pk_mul_f32 v[74:75], v[74:75], s[98:99] op_sel:[0,1] op_sel_hi:[1,1]
	v_pk_mul_f32 v[76:77], v[76:77], s[98:99] op_sel:[0,1] op_sel_hi:[1,1]
	v_pk_mul_f32 v[80:81], v[80:81], s[98:99] op_sel:[0,1] op_sel_hi:[1,1]
	v_pk_mul_f32 v[78:79], v[78:79], s[98:99] op_sel:[0,1] op_sel_hi:[1,1]
	v_pk_mul_f32 v[74:75], v[74:75], s[100:101] op_sel_hi:[1,0]
	v_pk_mul_f32 v[76:77], v[76:77], s[100:101] op_sel_hi:[1,0]
	v_pk_mul_f32 v[80:81], v[80:81], s[100:101] op_sel_hi:[1,0]
	v_pk_mul_f32 v[78:79], v[78:79], s[100:101] op_sel_hi:[1,0]
	v_exp_f32_e32 v74, v74
	v_exp_f32_e32 v75, v75
	v_exp_f32_e32 v76, v76
	v_exp_f32_e32 v77, v77
	v_exp_f32_e32 v80, v80
	v_exp_f32_e32 v81, v81
	v_exp_f32_e32 v78, v78
	v_exp_f32_e32 v79, v79
	v_pk_add_f32 v[74:75], v[74:75], s[100:101] op_sel:[0,1] op_sel_hi:[1,1]
	v_pk_add_f32 v[76:77], v[76:77], s[100:101] op_sel:[0,1] op_sel_hi:[1,1]
	v_pk_add_f32 v[80:81], v[80:81], s[100:101] op_sel:[0,1] op_sel_hi:[1,1]
	v_pk_add_f32 v[78:79], v[78:79], s[100:101] op_sel:[0,1] op_sel_hi:[1,1]
	v_rcp_f32_e32 v74, v74
	v_rcp_f32_e32 v75, v75
	v_rcp_f32_e32 v76, v76
	v_rcp_f32_e32 v77, v77
	v_rcp_f32_e32 v80, v80
	v_rcp_f32_e32 v81, v81
	v_rcp_f32_e32 v78, v78
	v_rcp_f32_e32 v79, v79
	v_pk_mul_f32 v[74:75], v[62:63], v[74:75]
	v_pk_mul_f32 v[76:77], v[64:65], v[76:77]
	v_pk_mul_f32 v[80:81], v[60:61], v[80:81]
	v_pk_mul_f32 v[78:79], v[58:59], v[78:79]

.LBB0_417:
	s_andn2_b64 vcc, exec, s[14:15]
	s_cbranch_vccnz .LBB0_421
	s_cmp_eq_u32 s16, 1
	s_cbranch_scc0 .LBB0_420
	s_mov_b32 s100, 0xbfb8aa3b
	s_mov_b32 s101, 1.0
	v_pk_mul_f32 v[74:75], v[62:63], s[100:101] op_sel_hi:[1,0]
	v_pk_mul_f32 v[76:77], v[58:59], s[100:101] op_sel_hi:[1,0]
	v_pk_mul_f32 v[78:79], v[64:65], s[100:101] op_sel_hi:[1,0]
	v_pk_mul_f32 v[80:81], v[60:61], s[100:101] op_sel_hi:[1,0]
	v_exp_f32_e32 v74, v74
	v_exp_f32_e32 v75, v75
	v_exp_f32_e32 v76, v76
	v_exp_f32_e32 v77, v77
	v_exp_f32_e32 v78, v78
	v_exp_f32_e32 v79, v79
	v_exp_f32_e32 v80, v80
	v_exp_f32_e32 v81, v81
	v_pk_add_f32 v[74:75], v[74:75], s[100:101] op_sel:[0,1] op_sel_hi:[1,1]
	v_pk_add_f32 v[76:77], v[76:77], s[100:101] op_sel:[0,1] op_sel_hi:[1,1]
	v_pk_add_f32 v[78:79], v[78:79], s[100:101] op_sel:[0,1] op_sel_hi:[1,1]
	v_pk_add_f32 v[80:81], v[80:81], s[100:101] op_sel:[0,1] op_sel_hi:[1,1]
	v_rcp_f32_e32 v74, v74
	v_rcp_f32_e32 v75, v75
	v_rcp_f32_e32 v76, v76
	v_rcp_f32_e32 v77, v77
	v_rcp_f32_e32 v78, v78
	v_rcp_f32_e32 v79, v79
	v_rcp_f32_e32 v80, v80
	v_rcp_f32_e32 v81, v81
	v_pk_mul_f32 v[62:63], v[62:63], v[74:75]
	v_pk_mul_f32 v[58:59], v[58:59], v[76:77]
	v_pk_mul_f32 v[64:65], v[64:65], v[78:79]
	v_pk_mul_f32 v[60:61], v[60:61], v[80:81]

.LBB0_421:
	v_cvt_pk_bf16_f32 v58, v74, v75
	v_cvt_pk_bf16_f32 v59, v76, v77
	v_cvt_pk_bf16_f32 v60, v78, v79
	v_cvt_pk_bf16_f32 v61, v80, v81
	global_store_dwordx4 v[92:93], v[58:61], off offset:256 nt
	s_cmp_lt_i32 s16, 2
	s_mov_b64 s[14:15], -1
	v_fmamk_f32 v58, v169, 0x3a800000, v235
	v_rsq_f32_e32 v74, v58
	s_nop 0
	v_pk_fma_f32 v[48:49], v[48:49], v[74:75], v[72:73] op_sel_hi:[1,0,1]
	v_pk_fma_f32 v[46:47], v[46:47], v[74:75], v[70:71] op_sel_hi:[1,0,1]
	v_pk_fma_f32 v[44:45], v[44:45], v[74:75], v[68:69] op_sel_hi:[1,0,1]
	v_pk_fma_f32 v[42:43], v[42:43], v[74:75], v[66:67] op_sel_hi:[1,0,1]
	s_cbranch_scc1 .LBB0_425
	v_mov_b64_e32 v[64:65], v[44:45]
	v_mov_b64_e32 v[60:61], v[48:49]
	s_cmp_eq_u32 s16, 2
	v_mov_b64_e32 v[62:63], v[42:43]
	v_mov_b64_e32 v[58:59], v[46:47]
	s_cbranch_scc0 .LBB0_424
	s_mov_b32 s98, 0x3d372713
	s_mov_b32 s99, 0x3fcc422a
	s_mov_b32 s100, 0xbfb8aa3b
	s_mov_b32 s101, 1.0
	v_pk_mul_f32 v[58:59], v[46:47], s[98:99] op_sel_hi:[1,0]
	v_pk_mul_f32 v[60:61], v[48:49], s[98:99] op_sel_hi:[1,0]
	v_pk_mul_f32 v[64:65], v[44:45], s[98:99] op_sel_hi:[1,0]
	v_pk_mul_f32 v[62:63], v[42:43], s[98:99] op_sel_hi:[1,0]
	v_pk_mul_f32 v[58:59], v[46:47], v[58:59]
	v_pk_mul_f32 v[60:61], v[48:49], v[60:61]
	v_pk_mul_f32 v[64:65], v[44:45], v[64:65]
	v_pk_mul_f32 v[62:63], v[42:43], v[62:63]
	v_pk_fma_f32 v[58:59], v[46:47], v[58:59], v[46:47]
	v_pk_fma_f32 v[60:61], v[48:49], v[60:61], v[48:49]
	v_pk_fma_f32 v[64:65], v[44:45], v[64:65], v[44:45]
	v_pk_fma_f32 v[62:63], v[42:43], v[62:63], v[42:43]
	v_pk_mul_f32 v[58:59], v[58:59], s[98:99] op_sel:[0,1] op_sel_hi:[1,1]
	v_pk_mul_f32 v[60:61], v[60:61], s[98:99] op_sel:[0,1] op_sel_hi:[1,1]
	v_pk_mul_f32 v[64:65], v[64:65], s[98:99] op_sel:[0,1] op_sel_hi:[1,1]
	v_pk_mul_f32 v[62:63], v[62:63], s[98:99] op_sel:[0,1] op_sel_hi:[1,1]
	v_pk_mul_f32 v[58:59], v[58:59], s[100:101] op_sel_hi:[1,0]
	v_pk_mul_f32 v[60:61], v[60:61], s[100:101] op_sel_hi:[1,0]
	v_pk_mul_f32 v[64:65], v[64:65], s[100:101] op_sel_hi:[1,0]
	v_pk_mul_f32 v[62:63], v[62:63], s[100:101] op_sel_hi:[1,0]
	v_exp_f32_e32 v58, v58
	v_exp_f32_e32 v59, v59
	v_exp_f32_e32 v60, v60
	v_exp_f32_e32 v61, v61
	v_exp_f32_e32 v64, v64
	v_exp_f32_e32 v65, v65
	v_exp_f32_e32 v62, v62
	v_exp_f32_e32 v63, v63
	v_pk_add_f32 v[58:59], v[58:59], s[100:101] op_sel:[0,1] op_sel_hi:[1,1]
	v_pk_add_f32 v[60:61], v[60:61], s[100:101] op_sel:[0,1] op_sel_hi:[1,1]
	v_pk_add_f32 v[64:65], v[64:65], s[100:101] op_sel:[0,1] op_sel_hi:[1,1]
	v_pk_add_f32 v[62:63], v[62:63], s[100:101] op_sel:[0,1] op_sel_hi:[1,1]
	v_rcp_f32_e32 v58, v58
	v_rcp_f32_e32 v59, v59
	v_rcp_f32_e32 v60, v60
	v_rcp_f32_e32 v61, v61
	v_rcp_f32_e32 v64, v64
	v_rcp_f32_e32 v65, v65
	v_rcp_f32_e32 v62, v62
	v_rcp_f32_e32 v63, v63
	v_pk_mul_f32 v[58:59], v[46:47], v[58:59]
	v_pk_mul_f32 v[60:61], v[48:49], v[60:61]
	v_pk_mul_f32 v[64:65], v[44:45], v[64:65]
	v_pk_mul_f32 v[62:63], v[42:43], v[62:63]

.LBB0_425:
	s_andn2_b64 vcc, exec, s[14:15]
	s_cbranch_vccnz .LBB0_429
	s_cmp_eq_u32 s16, 1
	s_cbranch_scc0 .LBB0_428
	s_mov_b32 s100, 0xbfb8aa3b
	s_mov_b32 s101, 1.0
	v_pk_mul_f32 v[58:59], v[46:47], s[100:101] op_sel_hi:[1,0]
	v_pk_mul_f32 v[60:61], v[42:43], s[100:101] op_sel_hi:[1,0]
	v_pk_mul_f32 v[62:63], v[48:49], s[100:101] op_sel_hi:[1,0]
	v_pk_mul_f32 v[64:65], v[44:45], s[100:101] op_sel_hi:[1,0]
	v_exp_f32_e32 v58, v58
	v_exp_f32_e32 v59, v59
	v_exp_f32_e32 v60, v60
	v_exp_f32_e32 v61, v61
	v_exp_f32_e32 v62, v62
	v_exp_f32_e32 v63, v63
	v_exp_f32_e32 v64, v64
	v_exp_f32_e32 v65, v65
	v_pk_add_f32 v[58:59], v[58:59], s[100:101] op_sel:[0,1] op_sel_hi:[1,1]
	v_pk_add_f32 v[60:61], v[60:61], s[100:101] op_sel:[0,1] op_sel_hi:[1,1]
	v_pk_add_f32 v[62:63], v[62:63], s[100:101] op_sel:[0,1] op_sel_hi:[1,1]
	v_pk_add_f32 v[64:65], v[64:65], s[100:101] op_sel:[0,1] op_sel_hi:[1,1]
	v_rcp_f32_e32 v58, v58
	v_rcp_f32_e32 v59, v59
	v_rcp_f32_e32 v60, v60
	v_rcp_f32_e32 v61, v61
	v_rcp_f32_e32 v62, v62
	v_rcp_f32_e32 v63, v63
	v_rcp_f32_e32 v64, v64
	v_rcp_f32_e32 v65, v65
	v_pk_mul_f32 v[46:47], v[46:47], v[58:59]
	v_pk_mul_f32 v[42:43], v[42:43], v[60:61]
	v_pk_mul_f32 v[48:49], v[48:49], v[62:63]
	v_pk_mul_f32 v[44:45], v[44:45], v[64:65]

.LBB0_429:
	v_add_u32_e32 v44, 0x90, v172
	v_mov_b64_e32 v[42:43], s[68:69]
	v_mad_i64_i32 v[42:43], s[0:1], v44, s9, v[42:43]
	v_lshl_add_u64 v[76:77], v[174:175], 1, v[42:43]
	v_cvt_pk_bf16_f32 v42, v58, v59
	v_cvt_pk_bf16_f32 v43, v60, v61
	v_cvt_pk_bf16_f32 v44, v62, v63
	v_cvt_pk_bf16_f32 v45, v64, v65
	global_store_dwordx4 v[76:77], v[42:45], off nt
	v_mov_b32_e32 v75, v74
	v_pk_fma_f32 v[38:39], v[38:39], v[74:75], v[54:55]
	v_mov_b32_e32 v42, v74
	v_mov_b32_e32 v43, v74
	v_pk_fma_f32 v[40:41], v[40:41], v[42:43], v[56:57]
	v_pk_fma_f32 v[36:37], v[36:37], v[42:43], v[52:53]
	v_pk_fma_f32 v[34:35], v[34:35], v[74:75], v[50:51]
	s_cmp_lt_i32 s16, 2
	s_mov_b64 s[14:15], -1
	s_cbranch_scc1 .LBB0_433
	v_mov_b64_e32 v[48:49], v[36:37]
	v_mov_b64_e32 v[44:45], v[40:41]
	s_cmp_eq_u32 s16, 2
	v_mov_b64_e32 v[46:47], v[34:35]
	v_mov_b64_e32 v[42:43], v[38:39]
	s_cbranch_scc0 .LBB0_432
	s_mov_b32 s98, 0x3d372713
	s_mov_b32 s99, 0x3fcc422a
	s_mov_b32 s100, 0xbfb8aa3b
	s_mov_b32 s101, 1.0
	v_pk_mul_f32 v[42:43], v[38:39], s[98:99] op_sel_hi:[1,0]
	v_pk_mul_f32 v[44:45], v[40:41], s[98:99] op_sel_hi:[1,0]
	v_pk_mul_f32 v[48:49], v[36:37], s[98:99] op_sel_hi:[1,0]
	v_pk_mul_f32 v[46:47], v[34:35], s[98:99] op_sel_hi:[1,0]
	v_pk_mul_f32 v[42:43], v[38:39], v[42:43]
	v_pk_mul_f32 v[44:45], v[40:41], v[44:45]
	v_pk_mul_f32 v[48:49], v[36:37], v[48:49]
	v_pk_mul_f32 v[46:47], v[34:35], v[46:47]
	v_pk_fma_f32 v[42:43], v[38:39], v[42:43], v[38:39]
	v_pk_fma_f32 v[44:45], v[40:41], v[44:45], v[40:41]
	v_pk_fma_f32 v[48:49], v[36:37], v[48:49], v[36:37]
	v_pk_fma_f32 v[46:47], v[34:35], v[46:47], v[34:35]
	v_pk_mul_f32 v[42:43], v[42:43], s[98:99] op_sel:[0,1] op_sel_hi:[1,1]
	v_pk_mul_f32 v[44:45], v[44:45], s[98:99] op_sel:[0,1] op_sel_hi:[1,1]
	v_pk_mul_f32 v[48:49], v[48:49], s[98:99] op_sel:[0,1] op_sel_hi:[1,1]
	v_pk_mul_f32 v[46:47], v[46:47], s[98:99] op_sel:[0,1] op_sel_hi:[1,1]
	v_pk_mul_f32 v[42:43], v[42:43], s[100:101] op_sel_hi:[1,0]
	v_pk_mul_f32 v[44:45], v[44:45], s[100:101] op_sel_hi:[1,0]
	v_pk_mul_f32 v[48:49], v[48:49], s[100:101] op_sel_hi:[1,0]
	v_pk_mul_f32 v[46:47], v[46:47], s[100:101] op_sel_hi:[1,0]
	v_exp_f32_e32 v42, v42
	v_exp_f32_e32 v43, v43
	v_exp_f32_e32 v44, v44
	v_exp_f32_e32 v45, v45
	v_exp_f32_e32 v48, v48
	v_exp_f32_e32 v49, v49
	v_exp_f32_e32 v46, v46
	v_exp_f32_e32 v47, v47
	v_pk_add_f32 v[42:43], v[42:43], s[100:101] op_sel:[0,1] op_sel_hi:[1,1]
	v_pk_add_f32 v[44:45], v[44:45], s[100:101] op_sel:[0,1] op_sel_hi:[1,1]
	v_pk_add_f32 v[48:49], v[48:49], s[100:101] op_sel:[0,1] op_sel_hi:[1,1]
	v_pk_add_f32 v[46:47], v[46:47], s[100:101] op_sel:[0,1] op_sel_hi:[1,1]
	v_rcp_f32_e32 v42, v42
	v_rcp_f32_e32 v43, v43
	v_rcp_f32_e32 v44, v44
	v_rcp_f32_e32 v45, v45
	v_rcp_f32_e32 v48, v48
	v_rcp_f32_e32 v49, v49
	v_rcp_f32_e32 v46, v46
	v_rcp_f32_e32 v47, v47
	v_pk_mul_f32 v[42:43], v[38:39], v[42:43]
	v_pk_mul_f32 v[44:45], v[40:41], v[44:45]
	v_pk_mul_f32 v[48:49], v[36:37], v[48:49]
	v_pk_mul_f32 v[46:47], v[34:35], v[46:47]

.LBB0_433:
	s_andn2_b64 vcc, exec, s[14:15]
	s_cbranch_vccnz .LBB0_437
	s_cmp_eq_u32 s16, 1
	s_cbranch_scc0 .LBB0_436
	s_mov_b32 s100, 0xbfb8aa3b
	s_mov_b32 s101, 1.0
	v_pk_mul_f32 v[42:43], v[38:39], s[100:101] op_sel_hi:[1,0]
	v_pk_mul_f32 v[44:45], v[34:35], s[100:101] op_sel_hi:[1,0]
	v_pk_mul_f32 v[46:47], v[40:41], s[100:101] op_sel_hi:[1,0]
	v_pk_mul_f32 v[48:49], v[36:37], s[100:101] op_sel_hi:[1,0]
	v_exp_f32_e32 v42, v42
	v_exp_f32_e32 v43, v43
	v_exp_f32_e32 v44, v44
	v_exp_f32_e32 v45, v45
	v_exp_f32_e32 v46, v46
	v_exp_f32_e32 v47, v47
	v_exp_f32_e32 v48, v48
	v_exp_f32_e32 v49, v49
	v_pk_add_f32 v[42:43], v[42:43], s[100:101] op_sel:[0,1] op_sel_hi:[1,1]
	v_pk_add_f32 v[44:45], v[44:45], s[100:101] op_sel:[0,1] op_sel_hi:[1,1]
	v_pk_add_f32 v[46:47], v[46:47], s[100:101] op_sel:[0,1] op_sel_hi:[1,1]
	v_pk_add_f32 v[48:49], v[48:49], s[100:101] op_sel:[0,1] op_sel_hi:[1,1]
	v_rcp_f32_e32 v42, v42
	v_rcp_f32_e32 v43, v43
	v_rcp_f32_e32 v44, v44
	v_rcp_f32_e32 v45, v45
	v_rcp_f32_e32 v46, v46
	v_rcp_f32_e32 v47, v47
	v_rcp_f32_e32 v48, v48
	v_rcp_f32_e32 v49, v49
	v_pk_mul_f32 v[38:39], v[38:39], v[42:43]
	v_pk_mul_f32 v[34:35], v[34:35], v[44:45]
	v_pk_mul_f32 v[40:41], v[40:41], v[46:47]
	v_pk_mul_f32 v[36:37], v[36:37], v[48:49]

.LBB0_437:
	v_cvt_pk_bf16_f32 v34, v42, v43
	v_cvt_pk_bf16_f32 v35, v44, v45
	v_cvt_pk_bf16_f32 v36, v46, v47
	v_cvt_pk_bf16_f32 v37, v48, v49
	global_store_dwordx4 v[76:77], v[34:37], off offset:256 nt
	s_cmp_lt_i32 s16, 2
	s_mov_b64 s[14:15], -1
	v_fmamk_f32 v34, v167, 0x3a800000, v235
	v_rsq_f32_e32 v42, v34
	s_nop 0
	v_pk_fma_f32 v[32:33], v[32:33], v[42:43], v[72:73] op_sel_hi:[1,0,1]
	v_pk_fma_f32 v[30:31], v[30:31], v[42:43], v[70:71] op_sel_hi:[1,0,1]
	v_pk_fma_f32 v[28:29], v[28:29], v[42:43], v[68:69] op_sel_hi:[1,0,1]
	v_pk_fma_f32 v[26:27], v[26:27], v[42:43], v[66:67] op_sel_hi:[1,0,1]
	s_cbranch_scc1 .LBB0_441
	v_mov_b64_e32 v[40:41], v[28:29]
	v_mov_b64_e32 v[36:37], v[32:33]
	s_cmp_eq_u32 s16, 2
	v_mov_b64_e32 v[38:39], v[26:27]
	v_mov_b64_e32 v[34:35], v[30:31]
	s_cbranch_scc0 .LBB0_440
	s_mov_b32 s98, 0x3d372713
	s_mov_b32 s99, 0x3fcc422a
	s_mov_b32 s100, 0xbfb8aa3b
	s_mov_b32 s101, 1.0
	v_pk_mul_f32 v[34:35], v[30:31], s[98:99] op_sel_hi:[1,0]
	v_pk_mul_f32 v[36:37], v[32:33], s[98:99] op_sel_hi:[1,0]
	v_pk_mul_f32 v[40:41], v[28:29], s[98:99] op_sel_hi:[1,0]
	v_pk_mul_f32 v[38:39], v[26:27], s[98:99] op_sel_hi:[1,0]
	v_pk_mul_f32 v[34:35], v[30:31], v[34:35]
	v_pk_mul_f32 v[36:37], v[32:33], v[36:37]
	v_pk_mul_f32 v[40:41], v[28:29], v[40:41]
	v_pk_mul_f32 v[38:39], v[26:27], v[38:39]
	v_pk_fma_f32 v[34:35], v[30:31], v[34:35], v[30:31]
	v_pk_fma_f32 v[36:37], v[32:33], v[36:37], v[32:33]
	v_pk_fma_f32 v[40:41], v[28:29], v[40:41], v[28:29]
	v_pk_fma_f32 v[38:39], v[26:27], v[38:39], v[26:27]
	v_pk_mul_f32 v[34:35], v[34:35], s[98:99] op_sel:[0,1] op_sel_hi:[1,1]
	v_pk_mul_f32 v[36:37], v[36:37], s[98:99] op_sel:[0,1] op_sel_hi:[1,1]
	v_pk_mul_f32 v[40:41], v[40:41], s[98:99] op_sel:[0,1] op_sel_hi:[1,1]
	v_pk_mul_f32 v[38:39], v[38:39], s[98:99] op_sel:[0,1] op_sel_hi:[1,1]
	v_pk_mul_f32 v[34:35], v[34:35], s[100:101] op_sel_hi:[1,0]
	v_pk_mul_f32 v[36:37], v[36:37], s[100:101] op_sel_hi:[1,0]
	v_pk_mul_f32 v[40:41], v[40:41], s[100:101] op_sel_hi:[1,0]
	v_pk_mul_f32 v[38:39], v[38:39], s[100:101] op_sel_hi:[1,0]
	v_exp_f32_e32 v34, v34
	v_exp_f32_e32 v35, v35
	v_exp_f32_e32 v36, v36
	v_exp_f32_e32 v37, v37
	v_exp_f32_e32 v40, v40
	v_exp_f32_e32 v41, v41
	v_exp_f32_e32 v38, v38
	v_exp_f32_e32 v39, v39
	v_pk_add_f32 v[34:35], v[34:35], s[100:101] op_sel:[0,1] op_sel_hi:[1,1]
	v_pk_add_f32 v[36:37], v[36:37], s[100:101] op_sel:[0,1] op_sel_hi:[1,1]
	v_pk_add_f32 v[40:41], v[40:41], s[100:101] op_sel:[0,1] op_sel_hi:[1,1]
	v_pk_add_f32 v[38:39], v[38:39], s[100:101] op_sel:[0,1] op_sel_hi:[1,1]
	v_rcp_f32_e32 v34, v34
	v_rcp_f32_e32 v35, v35
	v_rcp_f32_e32 v36, v36
	v_rcp_f32_e32 v37, v37
	v_rcp_f32_e32 v40, v40
	v_rcp_f32_e32 v41, v41
	v_rcp_f32_e32 v38, v38
	v_rcp_f32_e32 v39, v39
	v_pk_mul_f32 v[34:35], v[30:31], v[34:35]
	v_pk_mul_f32 v[36:37], v[32:33], v[36:37]
	v_pk_mul_f32 v[40:41], v[28:29], v[40:41]
	v_pk_mul_f32 v[38:39], v[26:27], v[38:39]

.LBB0_441:
	s_andn2_b64 vcc, exec, s[14:15]
	s_cbranch_vccnz .LBB0_445
	s_cmp_eq_u32 s16, 1
	s_cbranch_scc0 .LBB0_444
	s_mov_b32 s100, 0xbfb8aa3b
	s_mov_b32 s101, 1.0
	v_pk_mul_f32 v[34:35], v[30:31], s[100:101] op_sel_hi:[1,0]
	v_pk_mul_f32 v[36:37], v[26:27], s[100:101] op_sel_hi:[1,0]
	v_pk_mul_f32 v[38:39], v[32:33], s[100:101] op_sel_hi:[1,0]
	v_pk_mul_f32 v[40:41], v[28:29], s[100:101] op_sel_hi:[1,0]
	v_exp_f32_e32 v34, v34
	v_exp_f32_e32 v35, v35
	v_exp_f32_e32 v36, v36
	v_exp_f32_e32 v37, v37
	v_exp_f32_e32 v38, v38
	v_exp_f32_e32 v39, v39
	v_exp_f32_e32 v40, v40
	v_exp_f32_e32 v41, v41
	v_pk_add_f32 v[34:35], v[34:35], s[100:101] op_sel:[0,1] op_sel_hi:[1,1]
	v_pk_add_f32 v[36:37], v[36:37], s[100:101] op_sel:[0,1] op_sel_hi:[1,1]
	v_pk_add_f32 v[38:39], v[38:39], s[100:101] op_sel:[0,1] op_sel_hi:[1,1]
	v_pk_add_f32 v[40:41], v[40:41], s[100:101] op_sel:[0,1] op_sel_hi:[1,1]
	v_rcp_f32_e32 v34, v34
	v_rcp_f32_e32 v35, v35
	v_rcp_f32_e32 v36, v36
	v_rcp_f32_e32 v37, v37
	v_rcp_f32_e32 v38, v38
	v_rcp_f32_e32 v39, v39
	v_rcp_f32_e32 v40, v40
	v_rcp_f32_e32 v41, v41
	v_pk_mul_f32 v[30:31], v[30:31], v[34:35]
	v_pk_mul_f32 v[26:27], v[26:27], v[36:37]
	v_pk_mul_f32 v[32:33], v[32:33], v[38:39]
	v_pk_mul_f32 v[28:29], v[28:29], v[40:41]

.LBB0_445:
	v_add_u32_e32 v28, 0xa0, v172
	v_mov_b64_e32 v[26:27], s[68:69]
	v_mad_i64_i32 v[26:27], s[0:1], v28, s9, v[26:27]
	v_lshl_add_u64 v[44:45], v[174:175], 1, v[26:27]
	v_cvt_pk_bf16_f32 v26, v34, v35
	v_cvt_pk_bf16_f32 v27, v36, v37
	v_cvt_pk_bf16_f32 v28, v38, v39
	v_cvt_pk_bf16_f32 v29, v40, v41
	global_store_dwordx4 v[44:45], v[26:29], off nt
	v_mov_b32_e32 v43, v42
	v_pk_fma_f32 v[22:23], v[22:23], v[42:43], v[54:55]
	v_mov_b32_e32 v26, v42
	v_mov_b32_e32 v27, v42
	v_pk_fma_f32 v[24:25], v[24:25], v[26:27], v[56:57]
	v_pk_fma_f32 v[20:21], v[20:21], v[26:27], v[52:53]
	v_pk_fma_f32 v[18:19], v[18:19], v[42:43], v[50:51]
	s_cmp_lt_i32 s16, 2
	s_mov_b64 s[14:15], -1
	s_cbranch_scc1 .LBB0_449
	v_mov_b64_e32 v[32:33], v[20:21]
	v_mov_b64_e32 v[28:29], v[24:25]
	s_cmp_eq_u32 s16, 2
	v_mov_b64_e32 v[30:31], v[18:19]
	v_mov_b64_e32 v[26:27], v[22:23]
	s_cbranch_scc0 .LBB0_448
	s_mov_b32 s98, 0x3d372713
	s_mov_b32 s99, 0x3fcc422a
	s_mov_b32 s100, 0xbfb8aa3b
	s_mov_b32 s101, 1.0
	v_pk_mul_f32 v[26:27], v[22:23], s[98:99] op_sel_hi:[1,0]
	v_pk_mul_f32 v[28:29], v[24:25], s[98:99] op_sel_hi:[1,0]
	v_pk_mul_f32 v[32:33], v[20:21], s[98:99] op_sel_hi:[1,0]
	v_pk_mul_f32 v[30:31], v[18:19], s[98:99] op_sel_hi:[1,0]
	v_pk_mul_f32 v[26:27], v[22:23], v[26:27]
	v_pk_mul_f32 v[28:29], v[24:25], v[28:29]
	v_pk_mul_f32 v[32:33], v[20:21], v[32:33]
	v_pk_mul_f32 v[30:31], v[18:19], v[30:31]
	v_pk_fma_f32 v[26:27], v[22:23], v[26:27], v[22:23]
	v_pk_fma_f32 v[28:29], v[24:25], v[28:29], v[24:25]
	v_pk_fma_f32 v[32:33], v[20:21], v[32:33], v[20:21]
	v_pk_fma_f32 v[30:31], v[18:19], v[30:31], v[18:19]
	v_pk_mul_f32 v[26:27], v[26:27], s[98:99] op_sel:[0,1] op_sel_hi:[1,1]
	v_pk_mul_f32 v[28:29], v[28:29], s[98:99] op_sel:[0,1] op_sel_hi:[1,1]
	v_pk_mul_f32 v[32:33], v[32:33], s[98:99] op_sel:[0,1] op_sel_hi:[1,1]
	v_pk_mul_f32 v[30:31], v[30:31], s[98:99] op_sel:[0,1] op_sel_hi:[1,1]
	v_pk_mul_f32 v[26:27], v[26:27], s[100:101] op_sel_hi:[1,0]
	v_pk_mul_f32 v[28:29], v[28:29], s[100:101] op_sel_hi:[1,0]
	v_pk_mul_f32 v[32:33], v[32:33], s[100:101] op_sel_hi:[1,0]
	v_pk_mul_f32 v[30:31], v[30:31], s[100:101] op_sel_hi:[1,0]
	v_exp_f32_e32 v26, v26
	v_exp_f32_e32 v27, v27
	v_exp_f32_e32 v28, v28
	v_exp_f32_e32 v29, v29
	v_exp_f32_e32 v32, v32
	v_exp_f32_e32 v33, v33
	v_exp_f32_e32 v30, v30
	v_exp_f32_e32 v31, v31
	v_pk_add_f32 v[26:27], v[26:27], s[100:101] op_sel:[0,1] op_sel_hi:[1,1]
	v_pk_add_f32 v[28:29], v[28:29], s[100:101] op_sel:[0,1] op_sel_hi:[1,1]
	v_pk_add_f32 v[32:33], v[32:33], s[100:101] op_sel:[0,1] op_sel_hi:[1,1]
	v_pk_add_f32 v[30:31], v[30:31], s[100:101] op_sel:[0,1] op_sel_hi:[1,1]
	v_rcp_f32_e32 v26, v26
	v_rcp_f32_e32 v27, v27
	v_rcp_f32_e32 v28, v28
	v_rcp_f32_e32 v29, v29
	v_rcp_f32_e32 v32, v32
	v_rcp_f32_e32 v33, v33
	v_rcp_f32_e32 v30, v30
	v_rcp_f32_e32 v31, v31
	v_pk_mul_f32 v[26:27], v[22:23], v[26:27]
	v_pk_mul_f32 v[28:29], v[24:25], v[28:29]
	v_pk_mul_f32 v[32:33], v[20:21], v[32:33]
	v_pk_mul_f32 v[30:31], v[18:19], v[30:31]

.LBB0_449:
	s_andn2_b64 vcc, exec, s[14:15]
	s_cbranch_vccnz .LBB0_453
	s_cmp_eq_u32 s16, 1
	s_cbranch_scc0 .LBB0_452
	s_mov_b32 s100, 0xbfb8aa3b
	s_mov_b32 s101, 1.0
	v_pk_mul_f32 v[26:27], v[22:23], s[100:101] op_sel_hi:[1,0]
	v_pk_mul_f32 v[28:29], v[18:19], s[100:101] op_sel_hi:[1,0]
	v_pk_mul_f32 v[30:31], v[24:25], s[100:101] op_sel_hi:[1,0]
	v_pk_mul_f32 v[32:33], v[20:21], s[100:101] op_sel_hi:[1,0]
	v_exp_f32_e32 v26, v26
	v_exp_f32_e32 v27, v27
	v_exp_f32_e32 v28, v28
	v_exp_f32_e32 v29, v29
	v_exp_f32_e32 v30, v30
	v_exp_f32_e32 v31, v31
	v_exp_f32_e32 v32, v32
	v_exp_f32_e32 v33, v33
	v_pk_add_f32 v[26:27], v[26:27], s[100:101] op_sel:[0,1] op_sel_hi:[1,1]
	v_pk_add_f32 v[28:29], v[28:29], s[100:101] op_sel:[0,1] op_sel_hi:[1,1]
	v_pk_add_f32 v[30:31], v[30:31], s[100:101] op_sel:[0,1] op_sel_hi:[1,1]
	v_pk_add_f32 v[32:33], v[32:33], s[100:101] op_sel:[0,1] op_sel_hi:[1,1]
	v_rcp_f32_e32 v26, v26
	v_rcp_f32_e32 v27, v27
	v_rcp_f32_e32 v28, v28
	v_rcp_f32_e32 v29, v29
	v_rcp_f32_e32 v30, v30
	v_rcp_f32_e32 v31, v31
	v_rcp_f32_e32 v32, v32
	v_rcp_f32_e32 v33, v33
	v_pk_mul_f32 v[22:23], v[22:23], v[26:27]
	v_pk_mul_f32 v[18:19], v[18:19], v[28:29]
	v_pk_mul_f32 v[24:25], v[24:25], v[30:31]
	v_pk_mul_f32 v[20:21], v[20:21], v[32:33]

.LBB0_453:
	v_cvt_pk_bf16_f32 v18, v26, v27
	v_cvt_pk_bf16_f32 v19, v28, v29
	v_cvt_pk_bf16_f32 v20, v30, v31
	v_cvt_pk_bf16_f32 v21, v32, v33
	global_store_dwordx4 v[44:45], v[18:21], off offset:256 nt
	s_cmp_lt_i32 s16, 2
	s_mov_b64 s[14:15], -1
	v_fmamk_f32 v18, v165, 0x3a800000, v235
	v_rsq_f32_e32 v26, v18
	s_nop 0
	v_pk_fma_f32 v[16:17], v[16:17], v[26:27], v[72:73] op_sel_hi:[1,0,1]
	v_pk_fma_f32 v[14:15], v[14:15], v[26:27], v[70:71] op_sel_hi:[1,0,1]
	v_pk_fma_f32 v[12:13], v[12:13], v[26:27], v[68:69] op_sel_hi:[1,0,1]
	v_pk_fma_f32 v[10:11], v[10:11], v[26:27], v[66:67] op_sel_hi:[1,0,1]
	s_cbranch_scc1 .LBB0_457
	v_mov_b64_e32 v[24:25], v[12:13]
	v_mov_b64_e32 v[20:21], v[16:17]
	s_cmp_eq_u32 s16, 2
	v_mov_b64_e32 v[22:23], v[10:11]
	v_mov_b64_e32 v[18:19], v[14:15]
	s_cbranch_scc0 .LBB0_456
	s_mov_b32 s98, 0x3d372713
	s_mov_b32 s99, 0x3fcc422a
	s_mov_b32 s100, 0xbfb8aa3b
	s_mov_b32 s101, 1.0
	v_pk_mul_f32 v[18:19], v[14:15], s[98:99] op_sel_hi:[1,0]
	v_pk_mul_f32 v[20:21], v[16:17], s[98:99] op_sel_hi:[1,0]
	v_pk_mul_f32 v[24:25], v[12:13], s[98:99] op_sel_hi:[1,0]
	v_pk_mul_f32 v[22:23], v[10:11], s[98:99] op_sel_hi:[1,0]
	v_pk_mul_f32 v[18:19], v[14:15], v[18:19]
	v_pk_mul_f32 v[20:21], v[16:17], v[20:21]
	v_pk_mul_f32 v[24:25], v[12:13], v[24:25]
	v_pk_mul_f32 v[22:23], v[10:11], v[22:23]
	v_pk_fma_f32 v[18:19], v[14:15], v[18:19], v[14:15]
	v_pk_fma_f32 v[20:21], v[16:17], v[20:21], v[16:17]
	v_pk_fma_f32 v[24:25], v[12:13], v[24:25], v[12:13]
	v_pk_fma_f32 v[22:23], v[10:11], v[22:23], v[10:11]
	v_pk_mul_f32 v[18:19], v[18:19], s[98:99] op_sel:[0,1] op_sel_hi:[1,1]
	v_pk_mul_f32 v[20:21], v[20:21], s[98:99] op_sel:[0,1] op_sel_hi:[1,1]
	v_pk_mul_f32 v[24:25], v[24:25], s[98:99] op_sel:[0,1] op_sel_hi:[1,1]
	v_pk_mul_f32 v[22:23], v[22:23], s[98:99] op_sel:[0,1] op_sel_hi:[1,1]
	v_pk_mul_f32 v[18:19], v[18:19], s[100:101] op_sel_hi:[1,0]
	v_pk_mul_f32 v[20:21], v[20:21], s[100:101] op_sel_hi:[1,0]
	v_pk_mul_f32 v[24:25], v[24:25], s[100:101] op_sel_hi:[1,0]
	v_pk_mul_f32 v[22:23], v[22:23], s[100:101] op_sel_hi:[1,0]
	v_exp_f32_e32 v18, v18
	v_exp_f32_e32 v19, v19
	v_exp_f32_e32 v20, v20
	v_exp_f32_e32 v21, v21
	v_exp_f32_e32 v24, v24
	v_exp_f32_e32 v25, v25
	v_exp_f32_e32 v22, v22
	v_exp_f32_e32 v23, v23
	v_pk_add_f32 v[18:19], v[18:19], s[100:101] op_sel:[0,1] op_sel_hi:[1,1]
	v_pk_add_f32 v[20:21], v[20:21], s[100:101] op_sel:[0,1] op_sel_hi:[1,1]
	v_pk_add_f32 v[24:25], v[24:25], s[100:101] op_sel:[0,1] op_sel_hi:[1,1]
	v_pk_add_f32 v[22:23], v[22:23], s[100:101] op_sel:[0,1] op_sel_hi:[1,1]
	v_rcp_f32_e32 v18, v18
	v_rcp_f32_e32 v19, v19
	v_rcp_f32_e32 v20, v20
	v_rcp_f32_e32 v21, v21
	v_rcp_f32_e32 v24, v24
	v_rcp_f32_e32 v25, v25
	v_rcp_f32_e32 v22, v22
	v_rcp_f32_e32 v23, v23
	v_pk_mul_f32 v[18:19], v[14:15], v[18:19]
	v_pk_mul_f32 v[20:21], v[16:17], v[20:21]
	v_pk_mul_f32 v[24:25], v[12:13], v[24:25]
	v_pk_mul_f32 v[22:23], v[10:11], v[22:23]

.LBB0_457:
	s_andn2_b64 vcc, exec, s[14:15]
	s_cbranch_vccnz .LBB0_461
	s_cmp_eq_u32 s16, 1
	s_cbranch_scc0 .LBB0_460
	s_mov_b32 s100, 0xbfb8aa3b
	s_mov_b32 s101, 1.0
	v_pk_mul_f32 v[18:19], v[14:15], s[100:101] op_sel_hi:[1,0]
	v_pk_mul_f32 v[20:21], v[10:11], s[100:101] op_sel_hi:[1,0]
	v_pk_mul_f32 v[22:23], v[16:17], s[100:101] op_sel_hi:[1,0]
	v_pk_mul_f32 v[24:25], v[12:13], s[100:101] op_sel_hi:[1,0]
	v_exp_f32_e32 v18, v18
	v_exp_f32_e32 v19, v19
	v_exp_f32_e32 v20, v20
	v_exp_f32_e32 v21, v21
	v_exp_f32_e32 v22, v22
	v_exp_f32_e32 v23, v23
	v_exp_f32_e32 v24, v24
	v_exp_f32_e32 v25, v25
	v_pk_add_f32 v[18:19], v[18:19], s[100:101] op_sel:[0,1] op_sel_hi:[1,1]
	v_pk_add_f32 v[20:21], v[20:21], s[100:101] op_sel:[0,1] op_sel_hi:[1,1]
	v_pk_add_f32 v[22:23], v[22:23], s[100:101] op_sel:[0,1] op_sel_hi:[1,1]
	v_pk_add_f32 v[24:25], v[24:25], s[100:101] op_sel:[0,1] op_sel_hi:[1,1]
	v_rcp_f32_e32 v18, v18
	v_rcp_f32_e32 v19, v19
	v_rcp_f32_e32 v20, v20
	v_rcp_f32_e32 v21, v21
	v_rcp_f32_e32 v22, v22
	v_rcp_f32_e32 v23, v23
	v_rcp_f32_e32 v24, v24
	v_rcp_f32_e32 v25, v25
	v_pk_mul_f32 v[14:15], v[14:15], v[18:19]
	v_pk_mul_f32 v[10:11], v[10:11], v[20:21]
	v_pk_mul_f32 v[16:17], v[16:17], v[22:23]
	v_pk_mul_f32 v[12:13], v[12:13], v[24:25]

.LBB0_461:
	v_add_u32_e32 v12, 0xb0, v172
	v_mov_b64_e32 v[10:11], s[68:69]
	v_mad_i64_i32 v[10:11], s[0:1], v12, s9, v[10:11]
	v_lshl_add_u64 v[66:67], v[174:175], 1, v[10:11]
	v_cvt_pk_bf16_f32 v10, v18, v19
	v_cvt_pk_bf16_f32 v11, v20, v21
	v_cvt_pk_bf16_f32 v12, v22, v23
	v_cvt_pk_bf16_f32 v13, v24, v25
	global_store_dwordx4 v[66:67], v[10:13], off nt
	v_mov_b32_e32 v27, v26
	v_pk_fma_f32 v[6:7], v[6:7], v[26:27], v[54:55]
	v_mov_b32_e32 v10, v26
	v_mov_b32_e32 v11, v26
	v_pk_fma_f32 v[8:9], v[8:9], v[10:11], v[56:57]
	v_pk_fma_f32 v[4:5], v[4:5], v[10:11], v[52:53]
	v_pk_fma_f32 v[2:3], v[2:3], v[26:27], v[50:51]
	s_cmp_lt_i32 s16, 2
	s_mov_b64 s[14:15], -1
	s_cbranch_scc1 .LBB0_465
	v_mov_b64_e32 v[16:17], v[4:5]
	v_mov_b64_e32 v[12:13], v[8:9]
	s_cmp_eq_u32 s16, 2
	v_mov_b64_e32 v[14:15], v[2:3]
	v_mov_b64_e32 v[10:11], v[6:7]
	s_cbranch_scc0 .LBB0_464
	s_mov_b32 s98, 0x3d372713
	s_mov_b32 s99, 0x3fcc422a
	s_mov_b32 s100, 0xbfb8aa3b
	s_mov_b32 s101, 1.0
	v_pk_mul_f32 v[10:11], v[6:7], s[98:99] op_sel_hi:[1,0]
	v_pk_mul_f32 v[12:13], v[8:9], s[98:99] op_sel_hi:[1,0]
	v_pk_mul_f32 v[16:17], v[4:5], s[98:99] op_sel_hi:[1,0]
	v_pk_mul_f32 v[14:15], v[2:3], s[98:99] op_sel_hi:[1,0]
	v_pk_mul_f32 v[10:11], v[6:7], v[10:11]
	v_pk_mul_f32 v[12:13], v[8:9], v[12:13]
	v_pk_mul_f32 v[16:17], v[4:5], v[16:17]
	v_pk_mul_f32 v[14:15], v[2:3], v[14:15]
	v_pk_fma_f32 v[10:11], v[6:7], v[10:11], v[6:7]
	v_pk_fma_f32 v[12:13], v[8:9], v[12:13], v[8:9]
	v_pk_fma_f32 v[16:17], v[4:5], v[16:17], v[4:5]
	v_pk_fma_f32 v[14:15], v[2:3], v[14:15], v[2:3]
	v_pk_mul_f32 v[10:11], v[10:11], s[98:99] op_sel:[0,1] op_sel_hi:[1,1]
	v_pk_mul_f32 v[12:13], v[12:13], s[98:99] op_sel:[0,1] op_sel_hi:[1,1]
	v_pk_mul_f32 v[16:17], v[16:17], s[98:99] op_sel:[0,1] op_sel_hi:[1,1]
	v_pk_mul_f32 v[14:15], v[14:15], s[98:99] op_sel:[0,1] op_sel_hi:[1,1]
	v_pk_mul_f32 v[10:11], v[10:11], s[100:101] op_sel_hi:[1,0]
	v_pk_mul_f32 v[12:13], v[12:13], s[100:101] op_sel_hi:[1,0]
	v_pk_mul_f32 v[16:17], v[16:17], s[100:101] op_sel_hi:[1,0]
	v_pk_mul_f32 v[14:15], v[14:15], s[100:101] op_sel_hi:[1,0]
	v_exp_f32_e32 v10, v10
	v_exp_f32_e32 v11, v11
	v_exp_f32_e32 v12, v12
	v_exp_f32_e32 v13, v13
	v_exp_f32_e32 v16, v16
	v_exp_f32_e32 v17, v17
	v_exp_f32_e32 v14, v14
	v_exp_f32_e32 v15, v15
	v_pk_add_f32 v[10:11], v[10:11], s[100:101] op_sel:[0,1] op_sel_hi:[1,1]
	v_pk_add_f32 v[12:13], v[12:13], s[100:101] op_sel:[0,1] op_sel_hi:[1,1]
	v_pk_add_f32 v[16:17], v[16:17], s[100:101] op_sel:[0,1] op_sel_hi:[1,1]
	v_pk_add_f32 v[14:15], v[14:15], s[100:101] op_sel:[0,1] op_sel_hi:[1,1]
	v_rcp_f32_e32 v10, v10
	v_rcp_f32_e32 v11, v11
	v_rcp_f32_e32 v12, v12
	v_rcp_f32_e32 v13, v13
	v_rcp_f32_e32 v16, v16
	v_rcp_f32_e32 v17, v17
	v_rcp_f32_e32 v14, v14
	v_rcp_f32_e32 v15, v15
	v_pk_mul_f32 v[10:11], v[6:7], v[10:11]
	v_pk_mul_f32 v[12:13], v[8:9], v[12:13]
	v_pk_mul_f32 v[16:17], v[4:5], v[16:17]
	v_pk_mul_f32 v[14:15], v[2:3], v[14:15]

.LBB0_465:
	s_andn2_b64 vcc, exec, s[14:15]
	s_cbranch_vccnz .LBB0_469
	s_cmp_eq_u32 s16, 1
	s_cbranch_scc0 .LBB0_468
	s_mov_b32 s100, 0xbfb8aa3b
	s_mov_b32 s101, 1.0
	v_pk_mul_f32 v[10:11], v[6:7], s[100:101] op_sel_hi:[1,0]
	v_pk_mul_f32 v[12:13], v[2:3], s[100:101] op_sel_hi:[1,0]
	v_pk_mul_f32 v[14:15], v[8:9], s[100:101] op_sel_hi:[1,0]
	v_pk_mul_f32 v[16:17], v[4:5], s[100:101] op_sel_hi:[1,0]
	v_exp_f32_e32 v10, v10
	v_exp_f32_e32 v11, v11
	v_exp_f32_e32 v12, v12
	v_exp_f32_e32 v13, v13
	v_exp_f32_e32 v14, v14
	v_exp_f32_e32 v15, v15
	v_exp_f32_e32 v16, v16
	v_exp_f32_e32 v17, v17
	v_pk_add_f32 v[10:11], v[10:11], s[100:101] op_sel:[0,1] op_sel_hi:[1,1]
	v_pk_add_f32 v[12:13], v[12:13], s[100:101] op_sel:[0,1] op_sel_hi:[1,1]
	v_pk_add_f32 v[14:15], v[14:15], s[100:101] op_sel:[0,1] op_sel_hi:[1,1]
	v_pk_add_f32 v[16:17], v[16:17], s[100:101] op_sel:[0,1] op_sel_hi:[1,1]
	v_rcp_f32_e32 v10, v10
	v_rcp_f32_e32 v11, v11
	v_rcp_f32_e32 v12, v12
	v_rcp_f32_e32 v13, v13
	v_rcp_f32_e32 v14, v14
	v_rcp_f32_e32 v15, v15
	v_rcp_f32_e32 v16, v16
	v_rcp_f32_e32 v17, v17
	v_pk_mul_f32 v[6:7], v[6:7], v[10:11]
	v_pk_mul_f32 v[2:3], v[2:3], v[12:13]
	v_pk_mul_f32 v[8:9], v[8:9], v[14:15]
	v_pk_mul_f32 v[4:5], v[4:5], v[16:17]
